# GEMM epilogue: per-row rstd loads hoisted before the first store, 24 serializing vmcnt(0) waits removed
# speedup vs baseline: 1.0035x; 1.0035x over previous
;     __device__ __forceinline__ void operator()(const f32x4 (&acc)[2][2][4][2], const Unit& u, int wr, int wc, int fr, int fq) const {
;     ...
;         const int row0 = u.pm * BM + wr * 64 + fr;
;         const int col0 = colt + wc * 32 + 8 * fq;
;         bf16_t* base = (bf16_t*)(ws + ob); const bf16_t* aux1 = (const bf16_t*)(ws + WS_R1); const bf16_t* aux2 = (const bf16_t*)(ws + WS_R2);
;         const float* rsp = (const float*)(ws + oRS);
;         if (k == EK_PAIRMUL || k == EK_SWIGLU) {
; #pragma unroll
;             for (int ai = 0; ai < 2; ++ai)
; #pragma unroll
;                 for (int m = 0; m < 4; ++m) {
;                     bf16_t* rowp = base + (size_t)(row0 + ai * HALF + m * 16) * ld + col0;
;                     const float rr = use_rs ? rsp[row0 + ai * HALF + m * 16] : 1.f;
;     ...
;                     const float rr = use_rs ? rsp[row0 + ai * HALF + m * 16] : 1.f;
.LBB0_714:
	s_add_u32 s40, s82, s8
	v_lshl_add_u32 v140, s25, 8, v160
	v_add_u32_e32 v142, s31, v168
	s_addc_u32 s41, s83, s9
	s_add_i32 s8, s36, -1
	s_cmp_lt_u32 s8, 2
	v_ashrrev_i32_e32 v143, 31, v142
	s_mov_b64 s[8:9], -1
	v_ashrrev_i32_e32 v141, 31, v140
	s_cselect_b64 s[30:31], -1, 0
	s_cmp_eq_u32 s75, 1
	s_cbranch_scc1 .Lepi_rs_load
	s_cmp_eq_u32 s75, 15
	s_cbranch_scc0 .Lepi_rs_done
.Lepi_rs_load:
	v_lshl_add_u64 v[190:191], v[140:141], 2, s[22:23]
	global_load_dword v182, v[190:191], off
	global_load_dword v183, v[190:191], off offset:64
	global_load_dword v184, v[190:191], off offset:128
	global_load_dword v185, v[190:191], off offset:192
	global_load_dword v186, v[190:191], off offset:512
	global_load_dword v187, v[190:191], off offset:576
	global_load_dword v188, v[190:191], off offset:640
	global_load_dword v189, v[190:191], off offset:704
	s_waitcnt vmcnt(0)
.Lepi_rs_done:
	s_and_b64 vcc, exec, s[30:31]
	s_cbranch_vccnz .LBB0_717
	s_cmp_lt_i32 s75, 15
	s_cbranch_scc1 .LBB0_720
	s_cmp_eq_u32 s75, 15
	s_cselect_b64 s[8:9], -1, 0
	s_cbranch_execz .LBB0_721
	s_branch .LBB0_722

;     __device__ __forceinline__ void operator()(const f32x4 (&acc)[2][2][4][2], const Unit& u, int wr, int wc, int fr, int fq) const {
;     ...
;                     const float rr = use_rs ? rsp[row0 + ai * HALF + m * 16] : 1.f;
.LBB0_722:
	v_mov_b32_e32 v170, 1.0
	s_andn2_b64 vcc, exec, s[8:9]
	v_lshl_add_u64 v[144:145], v[140:141], 2, s[22:23]
	s_cbranch_vccnz .LBB0_724
	v_mov_b32_e32 v170, v182

;     __device__ __forceinline__ void operator()(const f32x4 (&acc)[2][2][4][2], const Unit& u, int wr, int wc, int fr, int fq) const {
;     ...
;                     const float rr = use_rs ? rsp[row0 + ai * HALF + m * 16] : 1.f;
; #pragma unroll
;                     for (int bj = 0; bj < 2; ++bj) {
;                         f32x4 v0 = acc[ai][bj][m][0], v1 = acc[ai][bj][m][1];
;                         const size_t off = roff + bj * HALF;
;                         if (k == EK_PLAIN) { v0 = v0 * (sc * rr); v1 = v1 * (sc * rr); }
.LBB0_731:
	v_mul_f32_e32 v146, s67, v170
	s_andn2_b64 vcc, exec, s[8:9]
	v_mov_b32_e32 v147, v146
	s_cbranch_vccnz .LBB0_733

; __device__ __forceinline__ float sigm(float x) { return __builtin_amdgcn_rcpf(1.0f + __builtin_amdgcn_exp2f(-1.4426950408889634f * x)); }
;     __device__ __forceinline__ void operator()(const f32x4 (&acc)[2][2][4][2], const Unit& u, int wr, int wc, int fr, int fq) const {
;     ...
;                     bf16_t* rowp = base + (size_t)(row0 + ai * HALF + m * 16) * ld + col0;
;                     const float rr = use_rs ? rsp[row0 + ai * HALF + m * 16] : 1.f;
;                     f32x4 a0 = acc[ai][0][m][0] * rr, a1 = acc[ai][0][m][1] * rr; const f32x4 b0 = acc[ai][1][m][0] * rr, b1 = acc[ai][1][m][1] * rr;
;                     if (k == EK_SWIGLU) {
; #pragma unroll
;                         for (int i = 0; i < 4; ++i) { a0[i] = a0[i] * sigm(a0[i]); a1[i] = a1[i] * sigm(a1[i]); }
.LBB0_746:
	v_mov_b32_e32 v146, 1.0
	s_andn2_b64 vcc, exec, s[8:9]
	v_lshl_add_u64 v[144:145], v[140:141], 2, s[22:23]
	s_cbranch_vccnz .LBB0_748
	v_mov_b32_e32 v146, v182
.LBB0_748:
	s_cmp_eq_u32 s36, 2
	s_cselect_b64 s[8:9], -1, 0
	s_cmp_lg_u32 s36, 2
	v_pk_mul_f32 v[128:129], v[128:129], v[146:147] op_sel_hi:[1,0]
	v_pk_mul_f32 v[126:127], v[126:127], v[146:147] op_sel_hi:[1,0]
	v_pk_mul_f32 v[124:125], v[124:125], v[146:147] op_sel_hi:[1,0]
	v_pk_mul_f32 v[122:123], v[122:123], v[146:147] op_sel_hi:[1,0]
	s_cbranch_scc1 .LBB0_750
	v_mul_f32_e32 v141, 0xbfb8aa3b, v126
	v_exp_f32_e32 v141, v141
	s_nop 0
	v_add_f32_e32 v141, 1.0, v141
	v_rcp_f32_e32 v148, v141
	v_mul_f32_e32 v141, 0xbfb8aa3b, v122
	v_exp_f32_e32 v141, v141
	s_nop 0
	v_add_f32_e32 v141, 1.0, v141
	v_rcp_f32_e32 v150, v141
	v_mul_f32_e32 v141, 0xbfb8aa3b, v127
	v_exp_f32_e32 v141, v141
	s_nop 0
	v_add_f32_e32 v141, 1.0, v141
	v_rcp_f32_e32 v149, v141
	v_mul_f32_e32 v141, 0xbfb8aa3b, v123
	v_exp_f32_e32 v141, v141
	v_pk_mul_f32 v[126:127], v[126:127], v[148:149]
	v_add_f32_e32 v141, 1.0, v141
	v_rcp_f32_e32 v151, v141
	v_mul_f32_e32 v141, 0xbfb8aa3b, v128
	v_exp_f32_e32 v141, v141
	v_pk_mul_f32 v[122:123], v[122:123], v[150:151]
	v_add_f32_e32 v141, 1.0, v141
	v_rcp_f32_e32 v152, v141
	v_mul_f32_e32 v141, 0xbfb8aa3b, v124
	v_exp_f32_e32 v141, v141
	s_nop 0
	v_add_f32_e32 v141, 1.0, v141
	v_rcp_f32_e32 v154, v141
	v_mul_f32_e32 v141, 0xbfb8aa3b, v129
	v_exp_f32_e32 v141, v141
	s_nop 0
	v_add_f32_e32 v141, 1.0, v141
	v_rcp_f32_e32 v153, v141
	v_mul_f32_e32 v141, 0xbfb8aa3b, v125
	v_exp_f32_e32 v141, v141
	v_pk_mul_f32 v[128:129], v[128:129], v[152:153]
	v_add_f32_e32 v141, 1.0, v141
	v_rcp_f32_e32 v155, v141
	s_nop 0
	v_pk_mul_f32 v[124:125], v[124:125], v[154:155]

;     __device__ __forceinline__ void operator()(const f32x4 (&acc)[2][2][4][2], const Unit& u, int wr, int wc, int fr, int fq) const {
;     ...
;                     const float rr = use_rs ? rsp[row0 + ai * HALF + m * 16] : 1.f;
.LBB0_754:
	s_andn2_b64 vcc, exec, s[8:9]
	v_mov_b32_e32 v170, 1.0
	s_cbranch_vccnz .LBB0_756
	v_mov_b32_e32 v170, v183

; __device__ __forceinline__ float sigm(float x) { return __builtin_amdgcn_rcpf(1.0f + __builtin_amdgcn_exp2f(-1.4426950408889634f * x)); }
;     __device__ __forceinline__ void operator()(const f32x4 (&acc)[2][2][4][2], const Unit& u, int wr, int wc, int fr, int fq) const {
;     ...
;                     const float rr = use_rs ? rsp[row0 + ai * HALF + m * 16] : 1.f;
;                     f32x4 a0 = acc[ai][0][m][0] * rr, a1 = acc[ai][0][m][1] * rr; const f32x4 b0 = acc[ai][1][m][0] * rr, b1 = acc[ai][1][m][1] * rr;
;                     if (k == EK_SWIGLU) {
; #pragma unroll
;                         for (int i = 0; i < 4; ++i) { a0[i] = a0[i] * sigm(a0[i]); a1[i] = a1[i] * sigm(a1[i]); }
.LBB0_778:
	s_andn2_b64 vcc, exec, s[16:17]
	v_mov_b32_e32 v116, 1.0
	s_cbranch_vccnz .LBB0_780
	v_mov_b32_e32 v116, v183
.LBB0_780:
	v_pk_mul_f32 v[112:113], v[112:113], v[116:117] op_sel_hi:[1,0]
	v_pk_mul_f32 v[110:111], v[110:111], v[116:117] op_sel_hi:[1,0]
	v_pk_mul_f32 v[108:109], v[108:109], v[116:117] op_sel_hi:[1,0]
	v_cndmask_b32_e64 v117, 0, 1, s[8:9]
	v_cmp_ne_u32_e64 s[40:41], 1, v117
	s_andn2_b64 vcc, exec, s[8:9]
	v_pk_mul_f32 v[106:107], v[106:107], v[116:117] op_sel_hi:[1,0]
	s_cbranch_vccnz .LBB0_782
	v_mul_f32_e32 v117, 0xbfb8aa3b, v110
	v_exp_f32_e32 v117, v117
	s_nop 0
	v_add_f32_e32 v117, 1.0, v117
	v_rcp_f32_e32 v118, v117
	v_mul_f32_e32 v117, 0xbfb8aa3b, v106
	v_exp_f32_e32 v117, v117
	s_nop 0
	v_add_f32_e32 v117, 1.0, v117
	v_rcp_f32_e32 v120, v117
	v_mul_f32_e32 v117, 0xbfb8aa3b, v111
	v_exp_f32_e32 v117, v117
	s_nop 0
	v_add_f32_e32 v117, 1.0, v117
	v_rcp_f32_e32 v119, v117
	v_mul_f32_e32 v117, 0xbfb8aa3b, v107
	v_exp_f32_e32 v117, v117
	v_pk_mul_f32 v[110:111], v[110:111], v[118:119]
	v_add_f32_e32 v117, 1.0, v117
	v_rcp_f32_e32 v121, v117
	v_mul_f32_e32 v117, 0xbfb8aa3b, v112
	v_exp_f32_e32 v117, v117
	v_pk_mul_f32 v[106:107], v[106:107], v[120:121]
	v_add_f32_e32 v117, 1.0, v117
	v_rcp_f32_e32 v122, v117
	v_mul_f32_e32 v117, 0xbfb8aa3b, v108
	v_exp_f32_e32 v117, v117
	s_nop 0
	v_add_f32_e32 v117, 1.0, v117
	v_rcp_f32_e32 v124, v117
	v_mul_f32_e32 v117, 0xbfb8aa3b, v113
	v_exp_f32_e32 v117, v117
	s_nop 0
	v_add_f32_e32 v117, 1.0, v117
	v_rcp_f32_e32 v123, v117
	v_mul_f32_e32 v117, 0xbfb8aa3b, v109
	v_exp_f32_e32 v117, v117
	v_pk_mul_f32 v[112:113], v[112:113], v[122:123]
	v_add_f32_e32 v117, 1.0, v117
	v_rcp_f32_e32 v125, v117
	s_nop 0
	v_pk_mul_f32 v[108:109], v[108:109], v[124:125]

;     __device__ __forceinline__ void operator()(const f32x4 (&acc)[2][2][4][2], const Unit& u, int wr, int wc, int fr, int fq) const {
;     ...
;                     const float rr = use_rs ? rsp[row0 + ai * HALF + m * 16] : 1.f;
.LBB0_786:
	s_andn2_b64 vcc, exec, s[8:9]
	v_mov_b32_e32 v170, 1.0
	s_cbranch_vccnz .LBB0_788
	v_mov_b32_e32 v170, v184

; __device__ __forceinline__ float sigm(float x) { return __builtin_amdgcn_rcpf(1.0f + __builtin_amdgcn_exp2f(-1.4426950408889634f * x)); }
;     __device__ __forceinline__ void operator()(const f32x4 (&acc)[2][2][4][2], const Unit& u, int wr, int wc, int fr, int fq) const {
;     ...
;                     const float rr = use_rs ? rsp[row0 + ai * HALF + m * 16] : 1.f;
;                     f32x4 a0 = acc[ai][0][m][0] * rr, a1 = acc[ai][0][m][1] * rr; const f32x4 b0 = acc[ai][1][m][0] * rr, b1 = acc[ai][1][m][1] * rr;
;                     if (k == EK_SWIGLU) {
; #pragma unroll
;                         for (int i = 0; i < 4; ++i) { a0[i] = a0[i] * sigm(a0[i]); a1[i] = a1[i] * sigm(a1[i]); }
.LBB0_810:
	s_andn2_b64 vcc, exec, s[8:9]
	v_mov_b32_e32 v98, 1.0
	s_cbranch_vccnz .LBB0_812
	v_mov_b32_e32 v98, v184
.LBB0_812:
	v_pk_mul_f32 v[96:97], v[96:97], v[98:99] op_sel_hi:[1,0]
	v_pk_mul_f32 v[94:95], v[94:95], v[98:99] op_sel_hi:[1,0]
	v_pk_mul_f32 v[92:93], v[92:93], v[98:99] op_sel_hi:[1,0]
	s_and_b64 vcc, exec, s[40:41]
	v_pk_mul_f32 v[90:91], v[90:91], v[98:99] op_sel_hi:[1,0]
	s_cbranch_vccnz .LBB0_814
	v_mul_f32_e32 v99, 0xbfb8aa3b, v94
	v_exp_f32_e32 v99, v99
	s_nop 0
	v_add_f32_e32 v99, 1.0, v99
	v_rcp_f32_e32 v100, v99
	v_mul_f32_e32 v99, 0xbfb8aa3b, v90
	v_exp_f32_e32 v99, v99
	s_nop 0
	v_add_f32_e32 v99, 1.0, v99
	v_rcp_f32_e32 v102, v99
	v_mul_f32_e32 v99, 0xbfb8aa3b, v95
	v_exp_f32_e32 v99, v99
	s_nop 0
	v_add_f32_e32 v99, 1.0, v99
	v_rcp_f32_e32 v101, v99
	v_mul_f32_e32 v99, 0xbfb8aa3b, v91
	v_exp_f32_e32 v99, v99
	v_pk_mul_f32 v[94:95], v[94:95], v[100:101]
	v_add_f32_e32 v99, 1.0, v99
	v_rcp_f32_e32 v103, v99
	v_mul_f32_e32 v99, 0xbfb8aa3b, v96
	v_exp_f32_e32 v99, v99
	v_pk_mul_f32 v[90:91], v[90:91], v[102:103]
	v_add_f32_e32 v99, 1.0, v99
	v_rcp_f32_e32 v104, v99
	v_mul_f32_e32 v99, 0xbfb8aa3b, v92
	v_exp_f32_e32 v99, v99
	s_nop 0
	v_add_f32_e32 v99, 1.0, v99
	v_rcp_f32_e32 v106, v99
	v_mul_f32_e32 v99, 0xbfb8aa3b, v97
	v_exp_f32_e32 v99, v99
	s_nop 0
	v_add_f32_e32 v99, 1.0, v99
	v_rcp_f32_e32 v105, v99
	v_mul_f32_e32 v99, 0xbfb8aa3b, v93
	v_exp_f32_e32 v99, v99
	v_pk_mul_f32 v[96:97], v[96:97], v[104:105]
	v_add_f32_e32 v99, 1.0, v99
	v_rcp_f32_e32 v107, v99
	s_nop 0
	v_pk_mul_f32 v[92:93], v[92:93], v[106:107]

;     __device__ __forceinline__ void operator()(const f32x4 (&acc)[2][2][4][2], const Unit& u, int wr, int wc, int fr, int fq) const {
;     ...
;                     const float rr = use_rs ? rsp[row0 + ai * HALF + m * 16] : 1.f;
.LBB0_818:
	s_andn2_b64 vcc, exec, s[8:9]
	v_mov_b32_e32 v170, 1.0
	s_cbranch_vccnz .LBB0_820
	v_mov_b32_e32 v170, v185

; __device__ __forceinline__ float sigm(float x) { return __builtin_amdgcn_rcpf(1.0f + __builtin_amdgcn_exp2f(-1.4426950408889634f * x)); }
;     __device__ __forceinline__ void operator()(const f32x4 (&acc)[2][2][4][2], const Unit& u, int wr, int wc, int fr, int fq) const {
;     ...
;                     const float rr = use_rs ? rsp[row0 + ai * HALF + m * 16] : 1.f;
;                     f32x4 a0 = acc[ai][0][m][0] * rr, a1 = acc[ai][0][m][1] * rr; const f32x4 b0 = acc[ai][1][m][0] * rr, b1 = acc[ai][1][m][1] * rr;
;                     if (k == EK_SWIGLU) {
; #pragma unroll
;                         for (int i = 0; i < 4; ++i) { a0[i] = a0[i] * sigm(a0[i]); a1[i] = a1[i] * sigm(a1[i]); }
.LBB0_842:
	s_andn2_b64 vcc, exec, s[8:9]
	v_mov_b32_e32 v82, 1.0
	s_cbranch_vccnz .LBB0_844
	v_mov_b32_e32 v82, v185
.LBB0_844:
	v_pk_mul_f32 v[80:81], v[80:81], v[82:83] op_sel_hi:[1,0]
	v_pk_mul_f32 v[78:79], v[78:79], v[82:83] op_sel_hi:[1,0]
	v_pk_mul_f32 v[76:77], v[76:77], v[82:83] op_sel_hi:[1,0]
	s_and_b64 vcc, exec, s[40:41]
	v_pk_mul_f32 v[74:75], v[74:75], v[82:83] op_sel_hi:[1,0]
	s_cbranch_vccnz .LBB0_846
	v_mul_f32_e32 v83, 0xbfb8aa3b, v78
	v_exp_f32_e32 v83, v83
	s_nop 0
	v_add_f32_e32 v83, 1.0, v83
	v_rcp_f32_e32 v84, v83
	v_mul_f32_e32 v83, 0xbfb8aa3b, v74
	v_exp_f32_e32 v83, v83
	s_nop 0
	v_add_f32_e32 v83, 1.0, v83
	v_rcp_f32_e32 v86, v83
	v_mul_f32_e32 v83, 0xbfb8aa3b, v79
	v_exp_f32_e32 v83, v83
	s_nop 0
	v_add_f32_e32 v83, 1.0, v83
	v_rcp_f32_e32 v85, v83
	v_mul_f32_e32 v83, 0xbfb8aa3b, v75
	v_exp_f32_e32 v83, v83
	v_pk_mul_f32 v[78:79], v[78:79], v[84:85]
	v_add_f32_e32 v83, 1.0, v83
	v_rcp_f32_e32 v87, v83
	v_mul_f32_e32 v83, 0xbfb8aa3b, v80
	v_exp_f32_e32 v83, v83
	v_pk_mul_f32 v[74:75], v[74:75], v[86:87]
	v_add_f32_e32 v83, 1.0, v83
	v_rcp_f32_e32 v88, v83
	v_mul_f32_e32 v83, 0xbfb8aa3b, v76
	v_exp_f32_e32 v83, v83
	s_nop 0
	v_add_f32_e32 v83, 1.0, v83
	v_rcp_f32_e32 v90, v83
	v_mul_f32_e32 v83, 0xbfb8aa3b, v81
	v_exp_f32_e32 v83, v83
	s_nop 0
	v_add_f32_e32 v83, 1.0, v83
	v_rcp_f32_e32 v89, v83
	v_mul_f32_e32 v83, 0xbfb8aa3b, v77
	v_exp_f32_e32 v83, v83
	v_pk_mul_f32 v[80:81], v[80:81], v[88:89]
	v_add_f32_e32 v83, 1.0, v83
	v_rcp_f32_e32 v91, v83
	s_nop 0
	v_pk_mul_f32 v[76:77], v[76:77], v[90:91]

;     __device__ __forceinline__ void operator()(const f32x4 (&acc)[2][2][4][2], const Unit& u, int wr, int wc, int fr, int fq) const {
;     ...
;                     const float rr = use_rs ? rsp[row0 + ai * HALF + m * 16] : 1.f;
.LBB0_850:
	s_andn2_b64 vcc, exec, s[8:9]
	v_mov_b32_e32 v170, 1.0
	s_cbranch_vccnz .LBB0_852
	v_mov_b32_e32 v170, v186

; __device__ __forceinline__ float sigm(float x) { return __builtin_amdgcn_rcpf(1.0f + __builtin_amdgcn_exp2f(-1.4426950408889634f * x)); }
;     __device__ __forceinline__ void operator()(const f32x4 (&acc)[2][2][4][2], const Unit& u, int wr, int wc, int fr, int fq) const {
;     ...
;                     const float rr = use_rs ? rsp[row0 + ai * HALF + m * 16] : 1.f;
;                     f32x4 a0 = acc[ai][0][m][0] * rr, a1 = acc[ai][0][m][1] * rr; const f32x4 b0 = acc[ai][1][m][0] * rr, b1 = acc[ai][1][m][1] * rr;
;                     if (k == EK_SWIGLU) {
; #pragma unroll
;                         for (int i = 0; i < 4; ++i) { a0[i] = a0[i] * sigm(a0[i]); a1[i] = a1[i] * sigm(a1[i]); }
.LBB0_874:
	s_andn2_b64 vcc, exec, s[8:9]
	v_mov_b32_e32 v66, 1.0
	s_cbranch_vccnz .LBB0_876
	v_mov_b32_e32 v66, v186
.LBB0_876:
	v_pk_mul_f32 v[62:63], v[62:63], v[66:67] op_sel_hi:[1,0]
	v_pk_mul_f32 v[60:61], v[60:61], v[66:67] op_sel_hi:[1,0]
	v_pk_mul_f32 v[58:59], v[58:59], v[66:67] op_sel_hi:[1,0]
	s_and_b64 vcc, exec, s[40:41]
	v_pk_mul_f32 v[56:57], v[56:57], v[66:67] op_sel_hi:[1,0]
	s_cbranch_vccnz .LBB0_878
	v_mul_f32_e32 v67, 0xbfb8aa3b, v60
	v_exp_f32_e32 v67, v67
	s_nop 0
	v_add_f32_e32 v67, 1.0, v67
	v_rcp_f32_e32 v68, v67
	v_mul_f32_e32 v67, 0xbfb8aa3b, v56
	v_exp_f32_e32 v67, v67
	s_nop 0
	v_add_f32_e32 v67, 1.0, v67
	v_rcp_f32_e32 v70, v67
	v_mul_f32_e32 v67, 0xbfb8aa3b, v61
	v_exp_f32_e32 v67, v67
	s_nop 0
	v_add_f32_e32 v67, 1.0, v67
	v_rcp_f32_e32 v69, v67
	v_mul_f32_e32 v67, 0xbfb8aa3b, v57
	v_exp_f32_e32 v67, v67
	v_pk_mul_f32 v[60:61], v[60:61], v[68:69]
	v_add_f32_e32 v67, 1.0, v67
	v_rcp_f32_e32 v71, v67
	v_mul_f32_e32 v67, 0xbfb8aa3b, v62
	v_exp_f32_e32 v67, v67
	v_pk_mul_f32 v[56:57], v[56:57], v[70:71]
	v_add_f32_e32 v67, 1.0, v67
	v_rcp_f32_e32 v72, v67
	v_mul_f32_e32 v67, 0xbfb8aa3b, v58
	v_exp_f32_e32 v67, v67
	s_nop 0
	v_add_f32_e32 v67, 1.0, v67
	v_rcp_f32_e32 v74, v67
	v_mul_f32_e32 v67, 0xbfb8aa3b, v63
	v_exp_f32_e32 v67, v67
	s_nop 0
	v_add_f32_e32 v67, 1.0, v67
	v_rcp_f32_e32 v73, v67
	v_mul_f32_e32 v67, 0xbfb8aa3b, v59
	v_exp_f32_e32 v67, v67
	v_pk_mul_f32 v[62:63], v[62:63], v[72:73]
	v_add_f32_e32 v67, 1.0, v67
	v_rcp_f32_e32 v75, v67
	s_nop 0
	v_pk_mul_f32 v[58:59], v[58:59], v[74:75]

;     __device__ __forceinline__ void operator()(const f32x4 (&acc)[2][2][4][2], const Unit& u, int wr, int wc, int fr, int fq) const {
;     ...
;                     const float rr = use_rs ? rsp[row0 + ai * HALF + m * 16] : 1.f;
.LBB0_882:
	s_andn2_b64 vcc, exec, s[8:9]
	v_mov_b32_e32 v170, 1.0
	s_cbranch_vccnz .LBB0_884
	v_mov_b32_e32 v170, v187

; __device__ __forceinline__ float sigm(float x) { return __builtin_amdgcn_rcpf(1.0f + __builtin_amdgcn_exp2f(-1.4426950408889634f * x)); }
;     __device__ __forceinline__ void operator()(const f32x4 (&acc)[2][2][4][2], const Unit& u, int wr, int wc, int fr, int fq) const {
;     ...
;                     const float rr = use_rs ? rsp[row0 + ai * HALF + m * 16] : 1.f;
;                     f32x4 a0 = acc[ai][0][m][0] * rr, a1 = acc[ai][0][m][1] * rr; const f32x4 b0 = acc[ai][1][m][0] * rr, b1 = acc[ai][1][m][1] * rr;
;                     if (k == EK_SWIGLU) {
; #pragma unroll
;                         for (int i = 0; i < 4; ++i) { a0[i] = a0[i] * sigm(a0[i]); a1[i] = a1[i] * sigm(a1[i]); }
.LBB0_906:
	s_andn2_b64 vcc, exec, s[8:9]
	v_mov_b32_e32 v48, 1.0
	s_cbranch_vccnz .LBB0_908
	v_mov_b32_e32 v48, v187
.LBB0_908:
	v_pk_mul_f32 v[46:47], v[46:47], v[48:49] op_sel_hi:[1,0]
	v_pk_mul_f32 v[44:45], v[44:45], v[48:49] op_sel_hi:[1,0]
	v_pk_mul_f32 v[42:43], v[42:43], v[48:49] op_sel_hi:[1,0]
	s_and_b64 vcc, exec, s[40:41]
	v_pk_mul_f32 v[40:41], v[40:41], v[48:49] op_sel_hi:[1,0]
	s_cbranch_vccnz .LBB0_910
	v_mul_f32_e32 v49, 0xbfb8aa3b, v44
	v_exp_f32_e32 v49, v49
	s_nop 0
	v_add_f32_e32 v49, 1.0, v49
	v_rcp_f32_e32 v50, v49
	v_mul_f32_e32 v49, 0xbfb8aa3b, v40
	v_exp_f32_e32 v49, v49
	s_nop 0
	v_add_f32_e32 v49, 1.0, v49
	v_rcp_f32_e32 v52, v49
	v_mul_f32_e32 v49, 0xbfb8aa3b, v45
	v_exp_f32_e32 v49, v49
	s_nop 0
	v_add_f32_e32 v49, 1.0, v49
	v_rcp_f32_e32 v51, v49
	v_mul_f32_e32 v49, 0xbfb8aa3b, v41
	v_exp_f32_e32 v49, v49
	v_pk_mul_f32 v[44:45], v[44:45], v[50:51]
	v_add_f32_e32 v49, 1.0, v49
	v_rcp_f32_e32 v53, v49
	v_mul_f32_e32 v49, 0xbfb8aa3b, v46
	v_exp_f32_e32 v49, v49
	v_pk_mul_f32 v[40:41], v[40:41], v[52:53]
	v_add_f32_e32 v49, 1.0, v49
	v_rcp_f32_e32 v54, v49
	v_mul_f32_e32 v49, 0xbfb8aa3b, v42
	v_exp_f32_e32 v49, v49
	s_nop 0
	v_add_f32_e32 v49, 1.0, v49
	v_rcp_f32_e32 v56, v49
	v_mul_f32_e32 v49, 0xbfb8aa3b, v47
	v_exp_f32_e32 v49, v49
	s_nop 0
	v_add_f32_e32 v49, 1.0, v49
	v_rcp_f32_e32 v55, v49
	v_mul_f32_e32 v49, 0xbfb8aa3b, v43
	v_exp_f32_e32 v49, v49
	v_pk_mul_f32 v[46:47], v[46:47], v[54:55]
	v_add_f32_e32 v49, 1.0, v49
	v_rcp_f32_e32 v57, v49
	s_nop 0
	v_pk_mul_f32 v[42:43], v[42:43], v[56:57]

;     __device__ __forceinline__ void operator()(const f32x4 (&acc)[2][2][4][2], const Unit& u, int wr, int wc, int fr, int fq) const {
;     ...
;                     const float rr = use_rs ? rsp[row0 + ai * HALF + m * 16] : 1.f;
.LBB0_914:
	s_andn2_b64 vcc, exec, s[8:9]
	v_mov_b32_e32 v170, 1.0
	s_cbranch_vccnz .LBB0_916
	v_mov_b32_e32 v170, v188

; __device__ __forceinline__ float sigm(float x) { return __builtin_amdgcn_rcpf(1.0f + __builtin_amdgcn_exp2f(-1.4426950408889634f * x)); }
;     __device__ __forceinline__ void operator()(const f32x4 (&acc)[2][2][4][2], const Unit& u, int wr, int wc, int fr, int fq) const {
;     ...
;                     const float rr = use_rs ? rsp[row0 + ai * HALF + m * 16] : 1.f;
;                     f32x4 a0 = acc[ai][0][m][0] * rr, a1 = acc[ai][0][m][1] * rr; const f32x4 b0 = acc[ai][1][m][0] * rr, b1 = acc[ai][1][m][1] * rr;
;                     if (k == EK_SWIGLU) {
; #pragma unroll
;                         for (int i = 0; i < 4; ++i) { a0[i] = a0[i] * sigm(a0[i]); a1[i] = a1[i] * sigm(a1[i]); }
.LBB0_938:
	s_andn2_b64 vcc, exec, s[8:9]
	v_mov_b32_e32 v32, 1.0
	s_cbranch_vccnz .LBB0_940
	v_mov_b32_e32 v32, v188
.LBB0_940:
	v_pk_mul_f32 v[30:31], v[30:31], v[32:33] op_sel_hi:[1,0]
	v_pk_mul_f32 v[28:29], v[28:29], v[32:33] op_sel_hi:[1,0]
	v_pk_mul_f32 v[26:27], v[26:27], v[32:33] op_sel_hi:[1,0]
	s_and_b64 vcc, exec, s[40:41]
	v_pk_mul_f32 v[24:25], v[24:25], v[32:33] op_sel_hi:[1,0]
	s_cbranch_vccnz .LBB0_942
	v_mul_f32_e32 v33, 0xbfb8aa3b, v28
	v_exp_f32_e32 v33, v33
	s_nop 0
	v_add_f32_e32 v33, 1.0, v33
	v_rcp_f32_e32 v34, v33
	v_mul_f32_e32 v33, 0xbfb8aa3b, v24
	v_exp_f32_e32 v33, v33
	s_nop 0
	v_add_f32_e32 v33, 1.0, v33
	v_rcp_f32_e32 v36, v33
	v_mul_f32_e32 v33, 0xbfb8aa3b, v29
	v_exp_f32_e32 v33, v33
	s_nop 0
	v_add_f32_e32 v33, 1.0, v33
	v_rcp_f32_e32 v35, v33
	v_mul_f32_e32 v33, 0xbfb8aa3b, v25
	v_exp_f32_e32 v33, v33
	v_pk_mul_f32 v[28:29], v[28:29], v[34:35]
	v_add_f32_e32 v33, 1.0, v33
	v_rcp_f32_e32 v37, v33
	v_mul_f32_e32 v33, 0xbfb8aa3b, v30
	v_exp_f32_e32 v33, v33
	v_pk_mul_f32 v[24:25], v[24:25], v[36:37]
	v_add_f32_e32 v33, 1.0, v33
	v_rcp_f32_e32 v38, v33
	v_mul_f32_e32 v33, 0xbfb8aa3b, v26
	v_exp_f32_e32 v33, v33
	s_nop 0
	v_add_f32_e32 v33, 1.0, v33
	v_rcp_f32_e32 v40, v33
	v_mul_f32_e32 v33, 0xbfb8aa3b, v31
	v_exp_f32_e32 v33, v33
	s_nop 0
	v_add_f32_e32 v33, 1.0, v33
	v_rcp_f32_e32 v39, v33
	v_mul_f32_e32 v33, 0xbfb8aa3b, v27
	v_exp_f32_e32 v33, v33
	v_pk_mul_f32 v[30:31], v[30:31], v[38:39]
	v_add_f32_e32 v33, 1.0, v33
	v_rcp_f32_e32 v41, v33
	s_nop 0
	v_pk_mul_f32 v[26:27], v[26:27], v[40:41]

;     __device__ __forceinline__ void operator()(const f32x4 (&acc)[2][2][4][2], const Unit& u, int wr, int wc, int fr, int fq) const {
;     ...
;                     const float rr = use_rs ? rsp[row0 + ai * HALF + m * 16] : 1.f;
.LBB0_946:
	s_andn2_b64 vcc, exec, s[8:9]
	v_mov_b32_e32 v158, 1.0
	s_cbranch_vccnz .LBB0_948
	v_mov_b32_e32 v158, v189

;     __device__ __forceinline__ void operator()(const f32x4 (&acc)[2][2][4][2], const Unit& u, int wr, int wc, int fr, int fq) const {
;     ...
;                     const float rr = use_rs ? rsp[row0 + ai * HALF + m * 16] : 1.f;
; #pragma unroll
;                     for (int bj = 0; bj < 2; ++bj) {
;                         f32x4 v0 = acc[ai][bj][m][0], v1 = acc[ai][bj][m][1];
;                         const size_t off = roff + bj * HALF;
;                         if (k == EK_PLAIN) { v0 = v0 * (sc * rr); v1 = v1 * (sc * rr); }
.LBB0_955:
	v_mul_f32_e32 v144, s67, v158
	s_andn2_b64 vcc, exec, s[8:9]
	v_mov_b32_e32 v145, v144
	s_cbranch_vccnz .LBB0_957

; __device__ __forceinline__ float sigm(float x) { return __builtin_amdgcn_rcpf(1.0f + __builtin_amdgcn_exp2f(-1.4426950408889634f * x)); }
;     __device__ __forceinline__ void operator()(const f32x4 (&acc)[2][2][4][2], const Unit& u, int wr, int wc, int fr, int fq) const {
;     ...
;                     const float rr = use_rs ? rsp[row0 + ai * HALF + m * 16] : 1.f;
;                     f32x4 a0 = acc[ai][0][m][0] * rr, a1 = acc[ai][0][m][1] * rr; const f32x4 b0 = acc[ai][1][m][0] * rr, b1 = acc[ai][1][m][1] * rr;
;                     if (k == EK_SWIGLU) {
; #pragma unroll
;                         for (int i = 0; i < 4; ++i) { a0[i] = a0[i] * sigm(a0[i]); a1[i] = a1[i] * sigm(a1[i]); }
.LBB0_970:
	s_andn2_b64 vcc, exec, s[8:9]
	v_mov_b32_e32 v16, 1.0
	s_cbranch_vccnz .LBB0_972
	v_mov_b32_e32 v16, v189
.LBB0_972:
	v_pk_mul_f32 v[14:15], v[14:15], v[16:17] op_sel_hi:[1,0]
	v_pk_mul_f32 v[12:13], v[12:13], v[16:17] op_sel_hi:[1,0]
	v_pk_mul_f32 v[10:11], v[10:11], v[16:17] op_sel_hi:[1,0]
	s_and_b64 vcc, exec, s[40:41]
	v_pk_mul_f32 v[8:9], v[8:9], v[16:17] op_sel_hi:[1,0]
	s_cbranch_vccnz .LBB0_974
	v_mul_f32_e32 v17, 0xbfb8aa3b, v12
	v_exp_f32_e32 v17, v17
	s_nop 0
	v_add_f32_e32 v17, 1.0, v17
	v_rcp_f32_e32 v18, v17
	v_mul_f32_e32 v17, 0xbfb8aa3b, v8
	v_exp_f32_e32 v17, v17
	s_nop 0
	v_add_f32_e32 v17, 1.0, v17
	v_rcp_f32_e32 v20, v17
	v_mul_f32_e32 v17, 0xbfb8aa3b, v13
	v_exp_f32_e32 v17, v17
	s_nop 0
	v_add_f32_e32 v17, 1.0, v17
	v_rcp_f32_e32 v19, v17
	v_mul_f32_e32 v17, 0xbfb8aa3b, v9
	v_exp_f32_e32 v17, v17
	v_pk_mul_f32 v[12:13], v[12:13], v[18:19]
	v_add_f32_e32 v17, 1.0, v17
	v_rcp_f32_e32 v21, v17
	v_mul_f32_e32 v17, 0xbfb8aa3b, v14
	v_exp_f32_e32 v17, v17
	v_pk_mul_f32 v[8:9], v[8:9], v[20:21]
	v_add_f32_e32 v17, 1.0, v17
	v_rcp_f32_e32 v22, v17
	v_mul_f32_e32 v17, 0xbfb8aa3b, v10
	v_exp_f32_e32 v17, v17
	s_nop 0
	v_add_f32_e32 v17, 1.0, v17
	v_rcp_f32_e32 v24, v17
	v_mul_f32_e32 v17, 0xbfb8aa3b, v15
	v_exp_f32_e32 v17, v17
	s_nop 0
	v_add_f32_e32 v17, 1.0, v17
	v_rcp_f32_e32 v23, v17
	v_mul_f32_e32 v17, 0xbfb8aa3b, v11
	v_exp_f32_e32 v17, v17
	v_pk_mul_f32 v[14:15], v[14:15], v[22:23]
	v_add_f32_e32 v17, 1.0, v17
	v_rcp_f32_e32 v25, v17
	s_nop 0
	v_pk_mul_f32 v[10:11], v[10:11], v[24:25]

; __device__ __forceinline__ float sigm(float x) { return __builtin_amdgcn_rcpf(1.0f + __builtin_amdgcn_exp2f(-1.4426950408889634f * x)); }
;     __device__ __forceinline__ void operator()(const f32x4 (&acc)[2][2][4][2], const Unit& u, int wr, int wc, int fr, int fq) const {
;     ...
;                         else if (k == EK_SIGMOID) {
; #pragma unroll
;                             for (int i = 0; i < 4; ++i) { v0[i] = sigm(v0[i] * rr); v1[i] = sigm(v1[i] * rr); }
.LBB0_977:
	s_and_b64 vcc, exec, s[30:31]
	s_cbranch_vccz .LBB0_979
	v_mul_f32_e32 v146, v126, v170
	v_mul_f32_e32 v146, 0xbfb8aa3b, v146
	v_mul_f32_e32 v147, v122, v170
	v_exp_f32_e32 v146, v146
	v_mul_f32_e32 v147, 0xbfb8aa3b, v147
	v_exp_f32_e32 v147, v147
	v_mul_f32_e32 v151, v123, v170
	v_add_f32_e32 v146, 1.0, v146
	v_rcp_f32_e32 v150, v146
	v_add_f32_e32 v146, 1.0, v147
	v_mul_f32_e32 v147, v127, v170
	v_mul_f32_e32 v147, 0xbfb8aa3b, v147
	v_exp_f32_e32 v147, v147
	v_mul_f32_e32 v151, 0xbfb8aa3b, v151
	v_exp_f32_e32 v153, v151
	v_rcp_f32_e32 v152, v146
	v_add_f32_e32 v146, 1.0, v147
	v_mul_f32_e32 v147, v128, v170
	v_rcp_f32_e32 v151, v146
	v_add_f32_e32 v146, 1.0, v153
	v_mul_f32_e32 v147, 0xbfb8aa3b, v147
	v_mul_f32_e32 v153, v124, v170
	v_exp_f32_e32 v147, v147
	v_mul_f32_e32 v153, 0xbfb8aa3b, v153
	v_exp_f32_e32 v155, v153
	v_rcp_f32_e32 v153, v146
	v_add_f32_e32 v146, 1.0, v147
	v_mul_f32_e32 v147, v129, v170
	v_rcp_f32_e32 v154, v146
	v_add_f32_e32 v146, 1.0, v155
	v_mul_f32_e32 v147, 0xbfb8aa3b, v147
	v_mul_f32_e32 v155, v125, v170
	v_exp_f32_e32 v147, v147
	v_mul_f32_e32 v155, 0xbfb8aa3b, v155
	v_exp_f32_e32 v157, v155
	v_rcp_f32_e32 v156, v146
	v_add_f32_e32 v146, 1.0, v147
	v_rcp_f32_e32 v155, v146
	v_add_f32_e32 v146, 1.0, v157
	v_rcp_f32_e32 v157, v146

; __device__ __forceinline__ float sigm(float x) { return __builtin_amdgcn_rcpf(1.0f + __builtin_amdgcn_exp2f(-1.4426950408889634f * x)); }
;     __device__ __forceinline__ void operator()(const f32x4 (&acc)[2][2][4][2], const Unit& u, int wr, int wc, int fr, int fq) const {
;     ...
;                         else if (k == EK_SIGMOID) {
; #pragma unroll
;                             for (int i = 0; i < 4; ++i) { v0[i] = sigm(v0[i] * rr); v1[i] = sigm(v1[i] * rr); }
.LBB0_987:
	s_and_b64 vcc, exec, s[30:31]
	s_cbranch_vccz .LBB0_989
	v_mul_f32_e32 v146, v110, v170
	v_mul_f32_e32 v146, 0xbfb8aa3b, v146
	v_mul_f32_e32 v147, v106, v170
	v_exp_f32_e32 v146, v146
	v_mul_f32_e32 v147, 0xbfb8aa3b, v147
	v_exp_f32_e32 v147, v147
	v_mul_f32_e32 v151, v107, v170
	v_add_f32_e32 v146, 1.0, v146
	v_rcp_f32_e32 v150, v146
	v_add_f32_e32 v146, 1.0, v147
	v_mul_f32_e32 v147, v111, v170
	v_mul_f32_e32 v147, 0xbfb8aa3b, v147
	v_exp_f32_e32 v147, v147
	v_mul_f32_e32 v151, 0xbfb8aa3b, v151
	v_exp_f32_e32 v153, v151
	v_rcp_f32_e32 v152, v146
	v_add_f32_e32 v146, 1.0, v147
	v_mul_f32_e32 v147, v112, v170
	v_rcp_f32_e32 v151, v146
	v_add_f32_e32 v146, 1.0, v153
	v_mul_f32_e32 v147, 0xbfb8aa3b, v147
	v_mul_f32_e32 v153, v108, v170
	v_exp_f32_e32 v147, v147
	v_mul_f32_e32 v153, 0xbfb8aa3b, v153
	v_exp_f32_e32 v155, v153
	v_rcp_f32_e32 v153, v146
	v_add_f32_e32 v146, 1.0, v147
	v_mul_f32_e32 v147, v113, v170
	v_rcp_f32_e32 v154, v146
	v_add_f32_e32 v146, 1.0, v155
	v_mul_f32_e32 v147, 0xbfb8aa3b, v147
	v_mul_f32_e32 v155, v109, v170
	v_exp_f32_e32 v147, v147
	v_mul_f32_e32 v155, 0xbfb8aa3b, v155
	v_exp_f32_e32 v157, v155
	v_rcp_f32_e32 v156, v146
	v_add_f32_e32 v146, 1.0, v147
	v_rcp_f32_e32 v155, v146
	v_add_f32_e32 v146, 1.0, v157
	v_rcp_f32_e32 v157, v146

; __device__ __forceinline__ float sigm(float x) { return __builtin_amdgcn_rcpf(1.0f + __builtin_amdgcn_exp2f(-1.4426950408889634f * x)); }
;     __device__ __forceinline__ void operator()(const f32x4 (&acc)[2][2][4][2], const Unit& u, int wr, int wc, int fr, int fq) const {
;     ...
;                         else if (k == EK_SIGMOID) {
; #pragma unroll
;                             for (int i = 0; i < 4; ++i) { v0[i] = sigm(v0[i] * rr); v1[i] = sigm(v1[i] * rr); }
.LBB0_997:
	s_and_b64 vcc, exec, s[30:31]
	s_cbranch_vccz .LBB0_999
	v_mul_f32_e32 v146, v94, v170
	v_mul_f32_e32 v146, 0xbfb8aa3b, v146
	v_mul_f32_e32 v147, v90, v170
	v_exp_f32_e32 v146, v146
	v_mul_f32_e32 v147, 0xbfb8aa3b, v147
	v_exp_f32_e32 v147, v147
	v_mul_f32_e32 v151, v91, v170
	v_add_f32_e32 v146, 1.0, v146
	v_rcp_f32_e32 v150, v146
	v_add_f32_e32 v146, 1.0, v147
	v_mul_f32_e32 v147, v95, v170
	v_mul_f32_e32 v147, 0xbfb8aa3b, v147
	v_exp_f32_e32 v147, v147
	v_mul_f32_e32 v151, 0xbfb8aa3b, v151
	v_exp_f32_e32 v153, v151
	v_rcp_f32_e32 v152, v146
	v_add_f32_e32 v146, 1.0, v147
	v_mul_f32_e32 v147, v96, v170
	v_rcp_f32_e32 v151, v146
	v_add_f32_e32 v146, 1.0, v153
	v_mul_f32_e32 v147, 0xbfb8aa3b, v147
	v_mul_f32_e32 v153, v92, v170
	v_exp_f32_e32 v147, v147
	v_mul_f32_e32 v153, 0xbfb8aa3b, v153
	v_exp_f32_e32 v155, v153
	v_rcp_f32_e32 v153, v146
	v_add_f32_e32 v146, 1.0, v147
	v_mul_f32_e32 v147, v97, v170
	v_rcp_f32_e32 v154, v146
	v_add_f32_e32 v146, 1.0, v155
	v_mul_f32_e32 v147, 0xbfb8aa3b, v147
	v_mul_f32_e32 v155, v93, v170
	v_exp_f32_e32 v147, v147
	v_mul_f32_e32 v155, 0xbfb8aa3b, v155
	v_exp_f32_e32 v157, v155
	v_rcp_f32_e32 v156, v146
	v_add_f32_e32 v146, 1.0, v147
	v_rcp_f32_e32 v155, v146
	v_add_f32_e32 v146, 1.0, v157
	v_rcp_f32_e32 v157, v146

; __device__ __forceinline__ float sigm(float x) { return __builtin_amdgcn_rcpf(1.0f + __builtin_amdgcn_exp2f(-1.4426950408889634f * x)); }
;     __device__ __forceinline__ void operator()(const f32x4 (&acc)[2][2][4][2], const Unit& u, int wr, int wc, int fr, int fq) const {
;     ...
;                         else if (k == EK_SIGMOID) {
; #pragma unroll
;                             for (int i = 0; i < 4; ++i) { v0[i] = sigm(v0[i] * rr); v1[i] = sigm(v1[i] * rr); }
.LBB0_1007:
	s_and_b64 vcc, exec, s[30:31]
	s_cbranch_vccz .LBB0_1009
	v_mul_f32_e32 v146, v78, v170
	v_mul_f32_e32 v146, 0xbfb8aa3b, v146
	v_mul_f32_e32 v147, v74, v170
	v_exp_f32_e32 v146, v146
	v_mul_f32_e32 v147, 0xbfb8aa3b, v147
	v_exp_f32_e32 v147, v147
	v_mul_f32_e32 v151, v75, v170
	v_add_f32_e32 v146, 1.0, v146
	v_rcp_f32_e32 v150, v146
	v_add_f32_e32 v146, 1.0, v147
	v_mul_f32_e32 v147, v79, v170
	v_mul_f32_e32 v147, 0xbfb8aa3b, v147
	v_exp_f32_e32 v147, v147
	v_mul_f32_e32 v151, 0xbfb8aa3b, v151
	v_exp_f32_e32 v153, v151
	v_rcp_f32_e32 v152, v146
	v_add_f32_e32 v146, 1.0, v147
	v_mul_f32_e32 v147, v80, v170
	v_rcp_f32_e32 v151, v146
	v_add_f32_e32 v146, 1.0, v153
	v_mul_f32_e32 v147, 0xbfb8aa3b, v147
	v_mul_f32_e32 v153, v76, v170
	v_exp_f32_e32 v147, v147
	v_mul_f32_e32 v153, 0xbfb8aa3b, v153
	v_exp_f32_e32 v155, v153
	v_rcp_f32_e32 v153, v146
	v_add_f32_e32 v146, 1.0, v147
	v_mul_f32_e32 v147, v81, v170
	v_rcp_f32_e32 v154, v146
	v_add_f32_e32 v146, 1.0, v155
	v_mul_f32_e32 v147, 0xbfb8aa3b, v147
	v_mul_f32_e32 v155, v77, v170
	v_exp_f32_e32 v147, v147
	v_mul_f32_e32 v155, 0xbfb8aa3b, v155
	v_exp_f32_e32 v157, v155
	v_rcp_f32_e32 v156, v146
	v_add_f32_e32 v146, 1.0, v147
	v_rcp_f32_e32 v155, v146
	v_add_f32_e32 v146, 1.0, v157
	v_rcp_f32_e32 v157, v146

; __device__ __forceinline__ float sigm(float x) { return __builtin_amdgcn_rcpf(1.0f + __builtin_amdgcn_exp2f(-1.4426950408889634f * x)); }
;     __device__ __forceinline__ void operator()(const f32x4 (&acc)[2][2][4][2], const Unit& u, int wr, int wc, int fr, int fq) const {
;     ...
;                         else if (k == EK_SIGMOID) {
; #pragma unroll
;                             for (int i = 0; i < 4; ++i) { v0[i] = sigm(v0[i] * rr); v1[i] = sigm(v1[i] * rr); }
.LBB0_1017:
	s_and_b64 vcc, exec, s[30:31]
	s_cbranch_vccz .LBB0_1019
	v_mul_f32_e32 v146, v60, v170
	v_mul_f32_e32 v146, 0xbfb8aa3b, v146
	v_mul_f32_e32 v147, v56, v170
	v_exp_f32_e32 v146, v146
	v_mul_f32_e32 v147, 0xbfb8aa3b, v147
	v_exp_f32_e32 v147, v147
	v_mul_f32_e32 v151, v57, v170
	v_add_f32_e32 v146, 1.0, v146
	v_rcp_f32_e32 v150, v146
	v_add_f32_e32 v146, 1.0, v147
	v_mul_f32_e32 v147, v61, v170
	v_mul_f32_e32 v147, 0xbfb8aa3b, v147
	v_exp_f32_e32 v147, v147
	v_mul_f32_e32 v151, 0xbfb8aa3b, v151
	v_exp_f32_e32 v153, v151
	v_rcp_f32_e32 v152, v146
	v_add_f32_e32 v146, 1.0, v147
	v_mul_f32_e32 v147, v62, v170
	v_rcp_f32_e32 v151, v146
	v_add_f32_e32 v146, 1.0, v153
	v_mul_f32_e32 v147, 0xbfb8aa3b, v147
	v_mul_f32_e32 v153, v58, v170
	v_exp_f32_e32 v147, v147
	v_mul_f32_e32 v153, 0xbfb8aa3b, v153
	v_exp_f32_e32 v155, v153
	v_rcp_f32_e32 v153, v146
	v_add_f32_e32 v146, 1.0, v147
	v_mul_f32_e32 v147, v63, v170
	v_rcp_f32_e32 v154, v146
	v_add_f32_e32 v146, 1.0, v155
	v_mul_f32_e32 v147, 0xbfb8aa3b, v147
	v_mul_f32_e32 v155, v59, v170
	v_exp_f32_e32 v147, v147
	v_mul_f32_e32 v155, 0xbfb8aa3b, v155
	v_exp_f32_e32 v157, v155
	v_rcp_f32_e32 v156, v146
	v_add_f32_e32 v146, 1.0, v147
	v_rcp_f32_e32 v155, v146
	v_add_f32_e32 v146, 1.0, v157
	v_rcp_f32_e32 v157, v146

; __device__ __forceinline__ float sigm(float x) { return __builtin_amdgcn_rcpf(1.0f + __builtin_amdgcn_exp2f(-1.4426950408889634f * x)); }
;     __device__ __forceinline__ void operator()(const f32x4 (&acc)[2][2][4][2], const Unit& u, int wr, int wc, int fr, int fq) const {
;     ...
;                         else if (k == EK_SIGMOID) {
; #pragma unroll
;                             for (int i = 0; i < 4; ++i) { v0[i] = sigm(v0[i] * rr); v1[i] = sigm(v1[i] * rr); }
.LBB0_1027:
	s_and_b64 vcc, exec, s[30:31]
	s_cbranch_vccz .LBB0_1029
	v_mul_f32_e32 v146, v44, v170
	v_mul_f32_e32 v146, 0xbfb8aa3b, v146
	v_mul_f32_e32 v147, v40, v170
	v_exp_f32_e32 v146, v146
	v_mul_f32_e32 v147, 0xbfb8aa3b, v147
	v_exp_f32_e32 v147, v147
	v_mul_f32_e32 v151, v41, v170
	v_add_f32_e32 v146, 1.0, v146
	v_rcp_f32_e32 v150, v146
	v_add_f32_e32 v146, 1.0, v147
	v_mul_f32_e32 v147, v45, v170
	v_mul_f32_e32 v147, 0xbfb8aa3b, v147
	v_exp_f32_e32 v147, v147
	v_mul_f32_e32 v151, 0xbfb8aa3b, v151
	v_exp_f32_e32 v153, v151
	v_rcp_f32_e32 v152, v146
	v_add_f32_e32 v146, 1.0, v147
	v_mul_f32_e32 v147, v46, v170
	v_rcp_f32_e32 v151, v146
	v_add_f32_e32 v146, 1.0, v153
	v_mul_f32_e32 v147, 0xbfb8aa3b, v147
	v_mul_f32_e32 v153, v42, v170
	v_exp_f32_e32 v147, v147
	v_mul_f32_e32 v153, 0xbfb8aa3b, v153
	v_exp_f32_e32 v155, v153
	v_rcp_f32_e32 v153, v146
	v_add_f32_e32 v146, 1.0, v147
	v_mul_f32_e32 v147, v47, v170
	v_rcp_f32_e32 v154, v146
	v_add_f32_e32 v146, 1.0, v155
	v_mul_f32_e32 v147, 0xbfb8aa3b, v147
	v_mul_f32_e32 v155, v43, v170
	v_exp_f32_e32 v147, v147
	v_mul_f32_e32 v155, 0xbfb8aa3b, v155
	v_exp_f32_e32 v157, v155
	v_rcp_f32_e32 v156, v146
	v_add_f32_e32 v146, 1.0, v147
	v_rcp_f32_e32 v155, v146
	v_add_f32_e32 v146, 1.0, v157
	v_rcp_f32_e32 v157, v146

; __device__ __forceinline__ float sigm(float x) { return __builtin_amdgcn_rcpf(1.0f + __builtin_amdgcn_exp2f(-1.4426950408889634f * x)); }
;     __device__ __forceinline__ void operator()(const f32x4 (&acc)[2][2][4][2], const Unit& u, int wr, int wc, int fr, int fq) const {
;     ...
;                         else if (k == EK_SIGMOID) {
; #pragma unroll
;                             for (int i = 0; i < 4; ++i) { v0[i] = sigm(v0[i] * rr); v1[i] = sigm(v1[i] * rr); }
.LBB0_1037:
	s_and_b64 vcc, exec, s[30:31]
	s_cbranch_vccz .LBB0_1039
	v_mul_f32_e32 v146, v28, v170
	v_mul_f32_e32 v146, 0xbfb8aa3b, v146
	v_mul_f32_e32 v147, v24, v170
	v_exp_f32_e32 v146, v146
	v_mul_f32_e32 v147, 0xbfb8aa3b, v147
	v_exp_f32_e32 v147, v147
	v_mul_f32_e32 v151, v25, v170
	v_add_f32_e32 v146, 1.0, v146
	v_rcp_f32_e32 v150, v146
	v_add_f32_e32 v146, 1.0, v147
	v_mul_f32_e32 v147, v29, v170
	v_mul_f32_e32 v147, 0xbfb8aa3b, v147
	v_exp_f32_e32 v147, v147
	v_mul_f32_e32 v151, 0xbfb8aa3b, v151
	v_exp_f32_e32 v153, v151
	v_rcp_f32_e32 v152, v146
	v_add_f32_e32 v146, 1.0, v147
	v_mul_f32_e32 v147, v30, v170
	v_rcp_f32_e32 v151, v146
	v_add_f32_e32 v146, 1.0, v153
	v_mul_f32_e32 v147, 0xbfb8aa3b, v147
	v_mul_f32_e32 v153, v26, v170
	v_exp_f32_e32 v147, v147
	v_mul_f32_e32 v153, 0xbfb8aa3b, v153
	v_exp_f32_e32 v155, v153
	v_rcp_f32_e32 v153, v146
	v_add_f32_e32 v146, 1.0, v147
	v_mul_f32_e32 v147, v31, v170
	v_rcp_f32_e32 v154, v146
	v_add_f32_e32 v146, 1.0, v155
	v_mul_f32_e32 v147, 0xbfb8aa3b, v147
	v_mul_f32_e32 v155, v27, v170
	v_exp_f32_e32 v147, v147
	v_mul_f32_e32 v155, 0xbfb8aa3b, v155
	v_exp_f32_e32 v157, v155
	v_rcp_f32_e32 v156, v146
	v_add_f32_e32 v146, 1.0, v147
	v_rcp_f32_e32 v155, v146
	v_add_f32_e32 v146, 1.0, v157
	v_rcp_f32_e32 v157, v146

; __device__ __forceinline__ float sigm(float x) { return __builtin_amdgcn_rcpf(1.0f + __builtin_amdgcn_exp2f(-1.4426950408889634f * x)); }
;     __device__ __forceinline__ void operator()(const f32x4 (&acc)[2][2][4][2], const Unit& u, int wr, int wc, int fr, int fq) const {
;     ...
;                         else if (k == EK_SIGMOID) {
; #pragma unroll
;                             for (int i = 0; i < 4; ++i) { v0[i] = sigm(v0[i] * rr); v1[i] = sigm(v1[i] * rr); }
.LBB0_1047:
	s_and_b64 vcc, exec, s[30:31]
	s_cbranch_vccz .LBB0_1049
	v_mul_f32_e32 v144, v12, v158
	v_mul_f32_e32 v144, 0xbfb8aa3b, v144
	v_mul_f32_e32 v145, v8, v158
	v_exp_f32_e32 v144, v144
	v_mul_f32_e32 v145, 0xbfb8aa3b, v145
	v_exp_f32_e32 v145, v145
	v_mul_f32_e32 v149, v9, v158
	v_add_f32_e32 v144, 1.0, v144
	v_rcp_f32_e32 v148, v144
	v_add_f32_e32 v144, 1.0, v145
	v_mul_f32_e32 v145, v13, v158
	v_mul_f32_e32 v145, 0xbfb8aa3b, v145
	v_exp_f32_e32 v145, v145
	v_mul_f32_e32 v149, 0xbfb8aa3b, v149
	v_exp_f32_e32 v151, v149
	v_rcp_f32_e32 v150, v144
	v_add_f32_e32 v144, 1.0, v145
	v_mul_f32_e32 v145, v14, v158
	v_rcp_f32_e32 v149, v144
	v_add_f32_e32 v144, 1.0, v151
	v_mul_f32_e32 v145, 0xbfb8aa3b, v145
	v_mul_f32_e32 v151, v10, v158
	v_exp_f32_e32 v145, v145
	v_mul_f32_e32 v151, 0xbfb8aa3b, v151
	v_exp_f32_e32 v153, v151
	v_rcp_f32_e32 v151, v144
	v_add_f32_e32 v144, 1.0, v145
	v_mul_f32_e32 v145, v15, v158
	v_rcp_f32_e32 v152, v144
	v_add_f32_e32 v144, 1.0, v153
	v_mul_f32_e32 v145, 0xbfb8aa3b, v145
	v_mul_f32_e32 v153, v11, v158
	v_exp_f32_e32 v145, v145
	v_mul_f32_e32 v153, 0xbfb8aa3b, v153
	v_exp_f32_e32 v155, v153
	v_rcp_f32_e32 v154, v144
	v_add_f32_e32 v144, 1.0, v145
	v_rcp_f32_e32 v153, v144
	v_add_f32_e32 v144, 1.0, v155
	v_rcp_f32_e32 v155, v144

; __device__ __forceinline__ unsigned pk2(float lo, float hi) { return pg8::cvt_pk_bf16(lo, hi); }
; __device__ __forceinline__ void load_q(bf16x8 (&qf)[6], const bf16_t* qn, const bf16_t* qr, const float* rp, int hi) {
; #pragma unroll
;     for (int d0 = 0; d0 < 4; ++d0) qf[d0] = *(const bf16x8*)(qn + d0 * 16 + hi * 8);
;     const u32x4 a = *(const u32x4*)(qr + hi * 8), b = *(const u32x4*)(qr + 16 + hi * 8);
;     const f32x4 c0 = *(const f32x4*)(rp + hi * 8), c1 = *(const f32x4*)(rp + hi * 8 + 4), s0 = *(const f32x4*)(rp + 16 + hi * 8), s1 = *(const f32x4*)(rp + 16 + hi * 8 + 4);
; __device__ __forceinline__ void prompt_unit(LAS unsigned char* lds, const Ptrs& P, int qloc0, int qglob0, int kloc0, int kglob0, int h, int qb) {
;     ...
;     l += __shfl_xor(l, 32);
;     const float inv = 1.0f / l;
;     bf16_t* orow = P.ATT + (size_t)(qglob0 + 32 * wid + r32) * 1024 + h * 64;
; #pragma unroll
;     for (int db = 0; db < 2; ++db)
; #pragma unroll
;         for (int g = 0; g < 4; ++g) { u32x2 w; w.x = pk2(o[db][4 * g] * inv, o[db][4 * g + 1] * inv); w.y = pk2(o[db][4 * g + 2] * inv, o[db][4 * g + 3] * inv);
;             *(u32x2*)(orow + 32 * db + 8 * g + 4 * hi) = w; }
.LBB0_1142:
	v_cmp_lt_i32_e32 vcc, v99, v100
	s_or_b32 s27, s27, s24
	s_nop 0
	v_cndmask_b32_e32 v32, v98, v99, vcc
	v_lshlrev_b32_e32 v32, 2, v32
	ds_bpermute_b32 v32, v32, v135
	s_barrier
	s_waitcnt lgkmcnt(0)
	v_lshlrev_b32_e32 v64, 3, v142
	s_mov_b64 s[66:67], 0
	v_add_f32_e32 v32, v135, v32
	v_div_scale_f32 v33, s[38:39], v32, v32, 1.0
	v_rcp_f32_e32 v34, v33
	s_nop 0
	v_fma_f32 v35, -v33, v34, 1.0
	v_fmac_f32_e32 v34, v35, v34
	v_div_scale_f32 v35, vcc, 1.0, v32, 1.0
	v_mul_f32_e32 v36, v35, v34
	v_fma_f32 v37, -v33, v36, v35
	v_fmac_f32_e32 v36, v37, v34
	v_fma_f32 v33, -v33, v36, v35
	v_div_fmas_f32 v33, v33, v34, v36
	v_div_fixup_f32 v34, v33, v32, 1.0
	v_add_u32_e32 v32, s27, v143
	v_ashrrev_i32_e32 v33, 31, v32
	v_lshlrev_b64 v[32:33], 11, v[32:33]
	v_mul_f32_e32 v16, v16, v34
	v_mul_f32_e32 v17, v17, v34
	v_lshl_add_u64 v[32:33], s[36:37], 0, v[32:33]
	v_cvt_pk_bf16_f32 v16, v16, v17
	v_mul_f32_e32 v17, v18, v34
	v_lshl_add_u64 v[32:33], v[32:33], 0, v[64:65]
	v_mul_f32_e32 v18, v19, v34
	v_cvt_pk_bf16_f32 v17, v17, v18
	global_store_dwordx2 v[32:33], v[16:17], off
	v_mul_f32_e32 v16, v20, v34
	v_mul_f32_e32 v17, v21, v34
	v_cvt_pk_bf16_f32 v16, v16, v17
	v_mul_f32_e32 v17, v22, v34
	v_mul_f32_e32 v18, v23, v34
	v_cvt_pk_bf16_f32 v17, v17, v18
	global_store_dwordx2 v[32:33], v[16:17], off offset:16
	v_mul_f32_e32 v16, v24, v34
	v_mul_f32_e32 v17, v25, v34
	v_cvt_pk_bf16_f32 v16, v16, v17
	v_mul_f32_e32 v17, v26, v34
	v_mul_f32_e32 v18, v27, v34
	v_cvt_pk_bf16_f32 v17, v17, v18
	global_store_dwordx2 v[32:33], v[16:17], off offset:32
	v_mul_f32_e32 v16, v28, v34
	v_mul_f32_e32 v17, v29, v34
	v_cvt_pk_bf16_f32 v16, v16, v17
	v_mul_f32_e32 v17, v30, v34
	v_mul_f32_e32 v0, v0, v34
	v_mul_f32_e32 v1, v1, v34
	v_mul_f32_e32 v18, v31, v34
	v_cvt_pk_bf16_f32 v17, v17, v18
	global_store_dwordx2 v[32:33], v[16:17], off offset:48
	v_cvt_pk_bf16_f32 v0, v0, v1
	v_mul_f32_e32 v1, v2, v34
	v_mul_f32_e32 v2, v3, v34
	v_cvt_pk_bf16_f32 v1, v1, v2
	global_store_dwordx2 v[32:33], v[0:1], off offset:64
	v_mul_f32_e32 v0, v4, v34
	v_mul_f32_e32 v1, v5, v34
	v_cvt_pk_bf16_f32 v0, v0, v1
	v_mul_f32_e32 v1, v6, v34
	v_mul_f32_e32 v2, v7, v34
	v_cvt_pk_bf16_f32 v1, v1, v2
	global_store_dwordx2 v[32:33], v[0:1], off offset:80
	v_mul_f32_e32 v0, v8, v34
	v_mul_f32_e32 v1, v9, v34
	v_cvt_pk_bf16_f32 v0, v0, v1
	v_mul_f32_e32 v1, v10, v34
	v_mul_f32_e32 v2, v11, v34
	v_cvt_pk_bf16_f32 v1, v1, v2
	global_store_dwordx2 v[32:33], v[0:1], off offset:96
	v_mul_f32_e32 v0, v12, v34
	v_mul_f32_e32 v1, v13, v34
	v_cvt_pk_bf16_f32 v0, v0, v1
	v_mul_f32_e32 v1, v14, v34
	s_and_b64 vcc, exec, s[64:65]
	v_mul_f32_e32 v2, v15, v34
	v_cvt_pk_bf16_f32 v1, v1, v2
	global_store_dwordx2 v[32:33], v[0:1], off offset:112
	s_cbranch_vccnz .LBB0_1139
.LBB0_1143:
	s_waitcnt vmcnt(0)
	v_mov_b32_e32 v16, v167
	s_and_b64 s[38:39], s[66:67], exec
	s_cselect_b32 s68, s3, s25
	v_readfirstlane_b32 s69, v16
	s_ashr_i32 s39, s69, 1
	s_lshl_b32 s27, s68, 8
	s_and_b32 s64, s39, 0xffffffe0
	v_mov_b32_e32 v0, s39
	s_movk_i32 s39, 0xffe0
	s_or_b32 s38, s27, s8
	v_bfi_b32 v143, s39, v0, v16
	v_add_u32_e32 v0, s38, v143
	v_and_b32_e32 v17, 31, v16
	s_add_i32 s64, s64, s27
	v_ashrrev_i32_e32 v1, 31, v0
	v_bfe_u32 v142, v16, 5, 1
	v_or_b32_e32 v4, s64, v17
	v_lshlrev_b64 v[2:3], 11, v[0:1]
	v_lshlrev_b64 v[0:1], 10, v[0:1]
	v_lshl_add_u64 v[2:3], s[16:17], 0, v[2:3]
	v_lshl_add_u64 v[0:1], s[22:23], 0, v[0:1]
	v_lshlrev_b32_e32 v4, 5, v4
	v_lshlrev_b32_e32 v64, 4, v142
	v_ashrrev_i32_e32 v5, 31, v4
	v_lshl_add_u64 v[2:3], v[2:3], 0, v[64:65]
	v_lshl_add_u64 v[0:1], v[0:1], 0, v[64:65]
	v_lshl_add_u64 v[4:5], v[4:5], 2, s[14:15]
	global_load_dwordx4 v[78:81], v[2:3], off
	global_load_dwordx4 v[74:77], v[2:3], off offset:32
	global_load_dwordx4 v[70:73], v[2:3], off offset:64
	s_waitcnt lgkmcnt(0)
	global_load_dwordx4 v[66:69], v[2:3], off offset:96
	global_load_dwordx4 v[8:11], v[0:1], off
	global_load_dwordx4 v[12:15], v[0:1], off offset:32
	v_lshlrev_b32_e32 v0, 5, v142
	v_mov_b32_e32 v1, v65
	v_lshl_add_u64 v[22:23], v[4:5], 0, v[0:1]
	global_load_dwordx4 v[0:3], v[22:23], off offset:16
	global_load_dwordx4 v[18:21], v[22:23], off
	global_load_dwordx4 v[4:7], v[22:23], off offset:80
	s_nop 0
	global_load_dwordx4 v[22:25], v[22:23], off offset:64
	v_mov_b32_e32 v90, v65
	v_mov_b32_e32 v91, v65
	v_mov_b32_e32 v92, v65
	v_mov_b32_e32 v93, v65
	s_waitcnt vmcnt(5)
	v_lshlrev_b32_e32 v27, 16, v8
	s_waitcnt vmcnt(4)
	v_lshlrev_b32_e32 v26, 16, v12
	s_waitcnt vmcnt(2)
	v_mov_b32_e32 v29, v18
	s_waitcnt vmcnt(0)
; __device__ __forceinline__ float bflo(unsigned w) { return __uint_as_float(w << 16); }
; __device__ __forceinline__ float bfhi(unsigned w) { return __uint_as_float(w & 0xffff0000u); }
; #define LAS __attribute__((address_space(3)))
; __device__ __forceinline__ void load_q(bf16x8 (&qf)[6], const bf16_t* qn, const bf16_t* qr, const float* rp, int hi) {
;     ...
;     const float x1[8] = {bflo(a.x), bfhi(a.x), bflo(a.y), bfhi(a.y), bflo(a.z), bfhi(a.z), bflo(a.w), bfhi(a.w)};
;     const float x2[8] = {bflo(b.x), bfhi(b.x), bflo(b.y), bfhi(b.y), bflo(b.z), bfhi(b.z), bflo(b.w), bfhi(b.w)};
;     const float cs[8] = {c0[0], c0[1], c0[2], c0[3], c1[0], c1[1], c1[2], c1[3]}, sn[8] = {s0[0], s0[1], s0[2], s0[3], s1[0], s1[1], s1[2], s1[3]};
;     float o1[8], o2[8];
; #pragma unroll
;     for (int j = 0; j < 8; ++j) { o1[j] = x1[j] * cs[j] - x2[j] * sn[j]; o2[j] = x1[j] * sn[j] + x2[j] * cs[j]; }
;     u32x4 w1 = (u32x4){pk2(o1[0], o1[1]), pk2(o1[2], o1[3]), pk2(o1[4], o1[5]), pk2(o1[6], o1[7])}, w2 = (u32x4){pk2(o2[0], o2[1]), pk2(o2[2], o2[3]), pk2(o2[4], o2[5]), pk2(o2[6], o2[7])};
;     qf[4] = __builtin_bit_cast(bf16x8, w1); qf[5] = __builtin_bit_cast(bf16x8, w2);
; __device__ __forceinline__ void prompt_unit(LAS unsigned char* lds, const Ptrs& P, int qloc0, int qglob0, int kloc0, int kglob0, int h, int qb) {
;     ...
;     const bf16_t* kn_src = P.Kn + (size_t)(kloc0 + (tid >> 3)) * 1024 + h * 64 + (tid & 7) * 8;
;     const bf16_t* vt_src = P.Vt + (size_t)(h * 64 + (tid >> 3)) * VT_LD + kloc0 + (tid & 7) * 8;
;     const bf16_t* kr_src = P.KR + (size_t)(kglob0 + ((tid & 255) >> 2)) * 32 + (tid & 3) * 8;
;     const int k_w = (tid >> 3) * KP + (tid & 7) * 16, r_w = ((tid & 255) >> 2) * KP + 128 + (tid & 3) * 16;
;     const int v_w = KB + (tid >> 3) * VP + ((tid & 7) >> 1) * 32 + (tid & 1) * 8;
;     u32x4 kreg, vreg, rreg = (u32x4){0u, 0u, 0u, 0u};
;     kreg = *(const u32x4*)kn_src; vreg = *(const u32x4*)vt_src; if (tid < 256) rreg = *(const u32x4*)kr_src;
;     *(LAS u32x4*)(lds + k_w) = kreg; if (tid < 256) *(LAS u32x4*)(lds + r_w) = rreg;
;     *(LAS u32x2*)(lds + v_w) = (u32x2){vreg.x, vreg.y}; *(LAS u32x2*)(lds + v_w + 16) = (u32x2){vreg.z, vreg.w};
;     __syncthreads();
;     float m = -1e30f, l = 0.f; f32x16 o[2];
; #pragma unroll
;     for (int r = 0; r < 16; ++r) { o[0][r] = 0.f; o[1][r] = 0.f; }
	v_mov_b32_e32 v28, v22
	v_pk_mul_f32 v[28:29], v[28:29], v[26:27]
	s_nop 0
	v_sub_f32_e32 v30, v29, v28
	v_mov_b32_e32 v28, v18
	v_mov_b32_e32 v29, v22
	v_pk_mul_f32 v[26:27], v[28:29], v[26:27]
	v_mov_b32_e32 v18, v23
	v_add_f32_e32 v31, v26, v27
	v_and_b32_e32 v27, 0xffff0000, v8
	v_and_b32_e32 v26, 0xffff0000, v12
	v_mov_b32_e32 v22, v19
	v_pk_mul_f32 v[28:29], v[18:19], v[26:27]
	v_pk_mul_f32 v[18:19], v[22:23], v[26:27]
	v_mov_b32_e32 v22, v24
	v_add_f32_e32 v26, v18, v19
	v_lshlrev_b32_e32 v19, 16, v9
	v_lshlrev_b32_e32 v18, 16, v13
	v_mov_b32_e32 v23, v20
	v_pk_mul_f32 v[22:23], v[22:23], v[18:19]
	v_and_b32_e32 v9, 0xffff0000, v9
	v_sub_f32_e32 v27, v23, v22
	v_mov_b32_e32 v22, v20
	v_mov_b32_e32 v23, v24
	v_and_b32_e32 v8, 0xffff0000, v13
	v_mov_b32_e32 v20, v25
	v_mov_b32_e32 v24, v21
	v_pk_mul_f32 v[18:19], v[22:23], v[18:19]
	v_pk_mul_f32 v[12:13], v[20:21], v[8:9]
	v_pk_mul_f32 v[8:9], v[24:25], v[8:9]
	v_add_f32_e32 v18, v18, v19
	v_sub_f32_e32 v19, v13, v12
	v_add_f32_e32 v20, v8, v9
	v_lshlrev_b32_e32 v9, 16, v10
	v_lshlrev_b32_e32 v8, 16, v14
	v_mov_b32_e32 v12, v4
	v_mov_b32_e32 v13, v0
	v_pk_mul_f32 v[12:13], v[12:13], v[8:9]
	v_sub_f32_e32 v28, v29, v28
	v_sub_f32_e32 v21, v13, v12
	v_mov_b32_e32 v12, v0
	v_mov_b32_e32 v13, v4
	v_pk_mul_f32 v[8:9], v[12:13], v[8:9]
	v_mov_b32_e32 v0, v5
	v_add_f32_e32 v22, v8, v9
	v_and_b32_e32 v9, 0xffff0000, v10
	v_and_b32_e32 v8, 0xffff0000, v14
	v_mov_b32_e32 v4, v1
	v_pk_mul_f32 v[12:13], v[0:1], v[8:9]
	v_pk_mul_f32 v[0:1], v[4:5], v[8:9]
	v_mov_b32_e32 v4, v6
	v_add_f32_e32 v8, v0, v1
	v_lshlrev_b32_e32 v1, 16, v11
	v_lshlrev_b32_e32 v0, 16, v15
	v_mov_b32_e32 v5, v2
	v_pk_mul_f32 v[4:5], v[4:5], v[0:1]
	v_sub_f32_e32 v10, v13, v12
	v_sub_f32_e32 v9, v5, v4
	v_mov_b32_e32 v4, v2
	v_mov_b32_e32 v5, v6
	v_pk_mul_f32 v[0:1], v[4:5], v[0:1]
	v_mov_b32_e32 v2, v7
	v_add_f32_e32 v12, v0, v1
	v_and_b32_e32 v1, 0xffff0000, v11
	v_and_b32_e32 v0, 0xffff0000, v15
	v_mov_b32_e32 v6, v3
	v_pk_mul_f32 v[4:5], v[2:3], v[0:1]
	v_pk_mul_f32 v[0:1], v[6:7], v[0:1]
	v_sub_f32_e32 v2, v5, v4
	v_add_f32_e32 v0, v0, v1
	v_cvt_pk_bf16_f32 v86, v30, v28
	v_cvt_pk_bf16_f32 v87, v27, v19
	v_cvt_pk_bf16_f32 v88, v21, v10
	v_cvt_pk_bf16_f32 v89, v9, v2
	v_cvt_pk_bf16_f32 v82, v31, v26
	v_cvt_pk_bf16_f32 v83, v18, v20
	v_cvt_pk_bf16_f32 v84, v22, v8
	v_cvt_pk_bf16_f32 v85, v12, v0
	v_ashrrev_i32_e32 v12, 3, v16
	v_add_u32_e32 v0, s8, v12
	v_ashrrev_i32_e32 v1, 31, v0
	v_and_b32_e32 v2, 7, v16
	v_lshlrev_b64 v[0:1], 11, v[0:1]
	v_lshlrev_b32_e32 v8, 4, v2
	v_add_u32_e32 v4, s26, v12
	v_mov_b64_e32 v[2:3], s[30:31]
	v_lshl_add_u64 v[0:1], s[28:29], 0, v[0:1]
	v_mov_b32_e32 v9, v65
	v_mad_i64_i32 v[2:3], s[38:39], v4, s77, v[2:3]
	v_lshl_add_u64 v[0:1], v[0:1], 0, v[8:9]
	v_lshl_add_u64 v[2:3], v[2:3], 0, v[8:9]
	global_load_dwordx4 v[4:7], v[0:1], off
	s_nop 0
	global_load_dwordx4 v[0:3], v[2:3], off
	s_movk_i32 s38, 0xff
	v_and_b32_e32 v9, 3, v16
	v_cmp_lt_i32_e32 vcc, s38, v16
	s_movk_i32 s38, 0x100
	v_bfe_u32 v13, v16, 2, 6
	v_cmp_gt_i32_e64 s[38:39], s38, v16
	v_lshlrev_b32_e32 v10, 4, v9
	s_and_saveexec_b64 s[64:65], s[38:39]
	s_cbranch_execz .LBB0_1145
	v_or_b32_e32 v14, s24, v13
	v_ashrrev_i32_e32 v15, 31, v14
	v_lshlrev_b64 v[14:15], 6, v[14:15]
	v_lshl_add_u64 v[14:15], s[12:13], 0, v[14:15]
	v_mov_b32_e32 v11, v65
	v_lshl_add_u64 v[14:15], v[14:15], 0, v[10:11]
	global_load_dwordx4 v[90:93], v[14:15], off
.LBB0_1145:
	s_or_b64 exec, exec, s[64:65]
	s_movk_i32 s64, 0xd0
	v_mad_u64_u32 v[134:135], s[64:65], v12, s64, v[8:9]
	v_mul_u32_u24_e32 v11, 0xd0, v13
	v_add_u32_e32 v14, 0, v134
	v_add_u32_e32 v146, v10, v11
	s_waitcnt vmcnt(1)
	ds_write_b128 v14, v[4:7]
	s_and_saveexec_b64 s[64:65], vcc
	s_xor_b64 s[64:65], exec, s[64:65]
	v_add_u32_e32 v146, v10, v11
	s_andn2_saveexec_b64 s[64:65], s[64:65]
	s_cbranch_execz .LBB0_1149
	v_add_u32_e32 v4, 0, v146
	s_waitcnt vmcnt(0)
	ds_write_b128 v4, v[90:93] offset:128
.LBB0_1149:
	s_or_b64 exec, exec, s[64:65]
	s_xor_b64 s[64:65], s[66:67], -1
	s_movk_i32 s67, 0x90
	v_mul_lo_u32 v4, v12, s67
	v_lshlrev_b32_e32 v6, 3, v16
	v_and_b32_e32 v5, 0x60, v8
	v_and_or_b32 v4, v6, 8, v4
	v_add_u32_e32 v148, v4, v5
	v_add_u32_e32 v4, 0, v148
	v_add_u32_e32 v4, 0x3000, v4
	s_lshl_b32 s66, s68, 2
	s_ashr_i32 s68, s69, 7
	s_waitcnt vmcnt(0)
	ds_write2_b64 v4, v[0:1], v[2:3] offset0:128 offset1:130
	v_lshlrev_b32_e32 v2, 4, v16
	s_add_i32 s69, s68, s66
	s_or_b32 s70, s66, 3
	v_mad_i64_i32 v[0:1], s[66:67], v12, s77, 0
	v_and_b32_e32 v2, 0x70, v2
	v_or_b32_e32 v0, v0, v2
	v_lshl_add_u64 v[136:137], s[40:41], 0, v[0:1]
	v_add_u32_e32 v0, s9, v13
	v_ashrrev_i32_e32 v1, 31, v0
	v_lshlrev_b64 v[0:1], 6, v[0:1]
	v_lshl_or_b32 v0, v9, 4, v0
	v_lshl_add_u64 v[138:139], s[96:97], 0, v[0:1]
	v_add_u32_e32 v0, s2, v12
	v_ashrrev_i32_e32 v1, 31, v0
	v_lshlrev_b64 v[0:1], 11, v[0:1]
	v_or_b32_e32 v0, v0, v2
	v_mul_u32_u24_e32 v147, 0xd0, v17
	v_mul_u32_u24_e32 v145, 0x90, v17
	v_add_u32_e32 v149, 0, v64
	v_lshl_add_u64 v[140:141], s[42:43], 0, v[0:1]
	s_mov_b32 s71, 0
	v_mov_b32_e32 v16, v65
	v_mov_b32_e32 v17, v65
	v_mov_b32_e32 v18, v65
	v_mov_b32_e32 v19, v65
	v_mov_b32_e32 v20, v65
	v_mov_b32_e32 v21, v65
	v_mov_b32_e32 v22, v65
	v_mov_b32_e32 v23, v65
	v_mov_b32_e32 v24, v65
	v_mov_b32_e32 v25, v65
	v_mov_b32_e32 v26, v65
	v_mov_b32_e32 v27, v65
	v_mov_b32_e32 v28, v65
	v_mov_b32_e32 v29, v65
	v_mov_b32_e32 v30, v65
	v_mov_b32_e32 v31, v65
	v_mov_b32_e32 v0, v65
	v_mov_b32_e32 v1, v65
	v_mov_b32_e32 v2, v65
	v_mov_b32_e32 v3, v65
	v_mov_b32_e32 v4, v65
	v_mov_b32_e32 v5, v65
	v_mov_b32_e32 v6, v65
	v_mov_b32_e32 v7, v65
	v_mov_b32_e32 v8, v65
	v_mov_b32_e32 v9, v65
	v_mov_b32_e32 v10, v65
	v_mov_b32_e32 v11, v65
	v_mov_b32_e32 v12, v65
	v_mov_b32_e32 v13, v65
	v_mov_b32_e32 v14, v65
	v_mov_b32_e32 v15, v65
	v_mov_b32_e32 v144, 0xf149f2ca
	v_mov_b32_e32 v135, 0
	s_waitcnt lgkmcnt(0)
	s_barrier
	s_branch .LBB0_1151
; #define LAS __attribute__((address_space(3)))
; __device__ __forceinline__ float fmax3(float a, float b, float c) { return fmaxf(fmaxf(a, b), c); }
; __device__ __forceinline__ void tile_core(const bf16x8 (&kf)[2][6], const bf16x8 (&vf)[2][4], const bf16x8 (&qf)[6], float& m, float& l, f32x16 (&o)[2], int nvalid, int hi) {
;     ...
;     for (int d0 = 0; d0 < 6; ++d0) { p0 = __builtin_amdgcn_mfma_f32_32x32x16_bf16(kf[0][d0], qf[d0], p0, 0, 0, 0); p1 = __builtin_amdgcn_mfma_f32_32x32x16_bf16(kf[1][d0], qf[d0], p1, 0, 0, 0); }
;     if (nvalid < 64) {
; #pragma unroll
;         for (int r = 0; r < 16; ++r) { const int kv = (r & 3) + 8 * (r >> 2) + 4 * hi; if (kv >= nvalid) p0[r] = -1e30f; if (kv + 32 >= nvalid) p1[r] = -1e30f; }
;     }
;     float rm = fmax3(p0[0], p0[1], p1[0]);
; #pragma unroll
;     for (int r = 1; r < 16; ++r) rm = fmax3(rm, p0[r], p1[r]);
;     rm = fmaxf(rm, __shfl_xor(rm, 32));
;     if (__any(rm > m + 8.0f)) { const float mn = fmaxf(m, rm), f = __builtin_amdgcn_exp2f(m - mn); l *= f; m = mn;
; #pragma unroll
;         for (int r = 0; r < 16; ++r) { o[0][r] *= f; o[1][r] *= f; } }
; __device__ __forceinline__ void prompt_unit(LAS unsigned char* lds, const Ptrs& P, int qloc0, int qglob0, int kloc0, int kglob0, int h, int qb) {
;     ...
;     for (int j = 0; j < NTL; ++j) {
;         const bool more = j + 1 < NTL;
;         if (more) { kreg = *(const u32x4*)(kn_src + (size_t)(j + 1) * 64 * 1024); vreg = *(const u32x4*)(vt_src + (j + 1) * 64); if (tid < 256) rreg = *(const u32x4*)(kr_src + (size_t)(j + 1) * 64 * 32); }
;         if (j <= cq) {
;             const LAS unsigned char* buf = lds + (j & 1) * BUFB;
;             bf16x8 kf[2][6], vf[2][4];
; #pragma unroll
;             for (int kb = 0; kb < 2; ++kb)
; #pragma unroll
;                 for (int d0 = 0; d0 < 6; ++d0) kf[kb][d0] = *(const LAS bf16x8*)(buf + (kb * 32 + r32) * KP + d0 * 32 + hi * 16);
; #pragma unroll
;             for (int db = 0; db < 2; ++db)
; #pragma unroll
;                 for (int s4 = 0; s4 < 4; ++s4) vf[db][s4] = *(const LAS bf16x8*)(buf + KB + (db * 32 + r32) * VP + s4 * 32 + hi * 16);
.LBB0_1150:
	s_or_b64 exec, exec, s[66:67]
	v_add_u32_e32 v32, s72, v148
	s_mov_b64 s[66:67], 0x20000
	v_add_u32_e32 v32, 0x3000, v32
	v_lshl_add_u64 v[136:137], v[136:137], 0, s[44:45]
	v_lshl_add_u64 v[138:139], v[138:139], 0, s[34:35]
	s_cmp_eq_u32 s70, s71
	v_lshl_add_u64 v[140:141], v[140:141], 0, s[66:67]
	s_waitcnt vmcnt(0)
	ds_write2_b64 v32, v[94:95], v[96:97] offset0:128 offset1:130
	s_waitcnt lgkmcnt(0)
	s_barrier
	s_cbranch_scc1 .LBB0_1159
.LBB0_1151:
	global_load_dwordx4 v[98:101], v[140:141], off
	global_load_dwordx4 v[94:97], v[136:137], off
	s_and_saveexec_b64 s[66:67], s[38:39]
	s_cbranch_execz .LBB0_1153
	global_load_dwordx4 v[90:93], v[138:139], off
.LBB0_1153:
	s_or_b64 exec, exec, s[66:67]
	s_cmp_gt_i32 s71, s69
	s_cbranch_scc1 .LBB0_1157
	s_bitcmp1_b32 s71, 0
	s_cselect_b32 s66, 0x5800, 0
	v_add_u32_e32 v114, s66, v149
	v_add_u32_e32 v115, v114, v147
	ds_read_b128 v[32:35], v115
	ds_read_b128 v[102:105], v115 offset:32
	s_waitcnt lgkmcnt(1)
	v_mfma_f32_32x32x16_bf16 v[48:63], v[32:35], v[78:81], 0
	ds_read_b128 v[32:35], v115 offset:6656
	ds_read_b128 v[106:109], v115 offset:6688
	s_waitcnt lgkmcnt(1)
	v_mfma_f32_32x32x16_bf16 v[32:47], v[32:35], v[78:81], 0
	v_mfma_f32_32x32x16_bf16 v[48:63], v[102:105], v[74:77], v[48:63]
	s_waitcnt lgkmcnt(0)
	v_mfma_f32_32x32x16_bf16 v[32:47], v[106:109], v[74:77], v[32:47]
	ds_read_b128 v[102:105], v115 offset:64
	ds_read_b128 v[106:109], v115 offset:96
	s_waitcnt lgkmcnt(1)
	v_mfma_f32_32x32x16_bf16 v[48:63], v[102:105], v[70:73], v[48:63]
	ds_read_b128 v[102:105], v115 offset:6720
	ds_read_b128 v[110:113], v115 offset:6752
	s_waitcnt lgkmcnt(1)
	v_mfma_f32_32x32x16_bf16 v[32:47], v[102:105], v[70:73], v[32:47]
	v_mfma_f32_32x32x16_bf16 v[48:63], v[106:109], v[66:69], v[48:63]
	ds_read_b128 v[102:105], v115 offset:128
	ds_read_b128 v[106:109], v115 offset:160
	s_waitcnt lgkmcnt(2)
	v_mfma_f32_32x32x16_bf16 v[32:47], v[110:113], v[66:69], v[32:47]
	s_waitcnt lgkmcnt(1)
	v_mfma_f32_32x32x16_bf16 v[48:63], v[102:105], v[86:89], v[48:63]
	ds_read_b128 v[102:105], v115 offset:6784
	ds_read_b128 v[110:113], v115 offset:6816
	s_waitcnt lgkmcnt(1)
	v_mfma_f32_32x32x16_bf16 v[32:47], v[102:105], v[86:89], v[32:47]
	v_add_u32_e32 v102, v114, v145
	ds_read_b128 v[130:133], v102 offset:13312
	ds_read_b128 v[126:129], v102 offset:13344
	ds_read_b128 v[122:125], v102 offset:13376
	ds_read_b128 v[114:117], v102 offset:13408
	v_mfma_f32_32x32x16_bf16 v[48:63], v[106:109], v[82:85], v[48:63]
	s_waitcnt lgkmcnt(4)
	v_mfma_f32_32x32x16_bf16 v[32:47], v[110:113], v[82:85], v[32:47]
	s_nop 11
	v_max3_f32 v103, v48, v49, v32
	v_max3_f32 v103, v103, v49, v33
	v_max3_f32 v103, v103, v50, v34
	v_max3_f32 v103, v103, v51, v35
	v_max3_f32 v103, v103, v52, v36
	v_max3_f32 v103, v103, v53, v37
	v_max3_f32 v103, v103, v54, v38
	v_max3_f32 v103, v103, v55, v39
	v_max3_f32 v103, v103, v56, v40
	v_max3_f32 v103, v103, v57, v41
	v_max3_f32 v103, v103, v58, v42
	v_max3_f32 v103, v103, v59, v43
	v_max3_f32 v103, v103, v60, v44
	v_max3_f32 v103, v103, v61, v45
	v_max3_f32 v103, v103, v62, v46
	v_max3_f32 v150, v103, v63, v47
	v_mbcnt_hi_u32_b32 v103, -1, v214
	v_and_b32_e32 v105, 64, v103
	v_xor_b32_e32 v104, 32, v103
	v_add_u32_e32 v105, 64, v105
	v_cmp_lt_i32_e32 vcc, v104, v105
	s_nop 1
	v_cndmask_b32_e32 v103, v103, v104, vcc
	v_lshlrev_b32_e32 v103, 2, v103
	ds_bpermute_b32 v151, v103, v150
	ds_read_b128 v[118:121], v102 offset:17920
	ds_read_b128 v[110:113], v102 offset:17952
	ds_read_b128 v[106:109], v102 offset:17984
	ds_read_b128 v[102:105], v102 offset:18016
	s_waitcnt lgkmcnt(4)
	v_max_f32_e32 v151, v151, v151
	v_max_f32_e32 v150, v150, v151
	v_add_f32_e32 v151, 0x41000000, v144
	v_cmp_gt_f32_e32 vcc, v150, v151
	s_cbranch_vccz .LBB0_1156
	v_max_f32_e32 v150, v150, v150
	v_max_f32_e32 v151, v144, v144
	v_max_f32_e32 v150, v151, v150
	v_sub_f32_e32 v144, v144, v150
	v_exp_f32_e32 v144, v144
	s_nop 0
	v_mul_f32_e32 v135, v135, v144
	v_pk_mul_f32 v[14:15], v[14:15], v[144:145] op_sel_hi:[1,0]
	v_pk_mul_f32 v[12:13], v[12:13], v[144:145] op_sel_hi:[1,0]
	v_pk_mul_f32 v[10:11], v[10:11], v[144:145] op_sel_hi:[1,0]
	v_pk_mul_f32 v[8:9], v[8:9], v[144:145] op_sel_hi:[1,0]
	v_pk_mul_f32 v[6:7], v[6:7], v[144:145] op_sel_hi:[1,0]
	v_pk_mul_f32 v[4:5], v[4:5], v[144:145] op_sel_hi:[1,0]
	v_pk_mul_f32 v[2:3], v[2:3], v[144:145] op_sel_hi:[1,0]
	v_pk_mul_f32 v[0:1], v[0:1], v[144:145] op_sel_hi:[1,0]
	v_pk_mul_f32 v[30:31], v[30:31], v[144:145] op_sel_hi:[1,0]
	v_pk_mul_f32 v[28:29], v[28:29], v[144:145] op_sel_hi:[1,0]
	v_pk_mul_f32 v[26:27], v[26:27], v[144:145] op_sel_hi:[1,0]
	v_pk_mul_f32 v[24:25], v[24:25], v[144:145] op_sel_hi:[1,0]
	v_pk_mul_f32 v[22:23], v[22:23], v[144:145] op_sel_hi:[1,0]
	v_pk_mul_f32 v[20:21], v[20:21], v[144:145] op_sel_hi:[1,0]
	v_pk_mul_f32 v[18:19], v[18:19], v[144:145] op_sel_hi:[1,0]
	v_pk_mul_f32 v[16:17], v[16:17], v[144:145] op_sel_hi:[1,0]
	v_mov_b32_e32 v144, v150
; #define LAS __attribute__((address_space(3)))
; __device__ __forceinline__ unsigned pk2(float lo, float hi) { return pg8::cvt_pk_bf16(lo, hi); }
; __device__ __forceinline__ void tile_core(const bf16x8 (&kf)[2][6], const bf16x8 (&vf)[2][4], const bf16x8 (&qf)[6], float& m, float& l, f32x16 (&o)[2], int nvalid, int hi) {
;     ...
;     float s = 0.f;
; #pragma unroll
;     for (int r = 0; r < 16; ++r) { p0[r] = __builtin_amdgcn_exp2f(p0[r] - m); p1[r] = __builtin_amdgcn_exp2f(p1[r] - m); s += p0[r] + p1[r]; }
;     l += s;
;     bf16x8 pa[4];
;     { u32x4 w;
;       w = (u32x4){pk2(p0[0], p0[1]), pk2(p0[2], p0[3]), pk2(p0[4], p0[5]), pk2(p0[6], p0[7])}; pa[0] = __builtin_bit_cast(bf16x8, w);
;       w = (u32x4){pk2(p0[8], p0[9]), pk2(p0[10], p0[11]), pk2(p0[12], p0[13]), pk2(p0[14], p0[15])}; pa[1] = __builtin_bit_cast(bf16x8, w);
;       w = (u32x4){pk2(p1[0], p1[1]), pk2(p1[2], p1[3]), pk2(p1[4], p1[5]), pk2(p1[6], p1[7])}; pa[2] = __builtin_bit_cast(bf16x8, w);
;       w = (u32x4){pk2(p1[8], p1[9]), pk2(p1[10], p1[11]), pk2(p1[12], p1[13]), pk2(p1[14], p1[15])}; pa[3] = __builtin_bit_cast(bf16x8, w); }
; #pragma unroll
;     for (int db = 0; db < 2; ++db)
; #pragma unroll
;         for (int s4 = 0; s4 < 4; ++s4) o[db] = __builtin_amdgcn_mfma_f32_32x32x16_bf16(vf[db][s4], pa[s4], o[db], 0, 0, 0);
; __device__ __forceinline__ void prompt_unit(LAS unsigned char* lds, const Ptrs& P, int qloc0, int qglob0, int kloc0, int kglob0, int h, int qb) {
;     ...
;         if (more) { LAS unsigned char* nb = lds + ((j + 1) & 1) * BUFB;
;             *(LAS u32x4*)(nb + k_w) = kreg; if (tid < 256) *(LAS u32x4*)(nb + r_w) = rreg;
;             *(LAS u32x2*)(nb + v_w) = (u32x2){vreg.x, vreg.y}; *(LAS u32x2*)(nb + v_w + 16) = (u32x2){vreg.z, vreg.w}; }
;         __syncthreads();
.LBB0_1156:
	v_sub_f32_e32 v32, v32, v144
	v_exp_f32_e32 v159, v32
	v_sub_f32_e32 v32, v49, v144
	v_exp_f32_e32 v160, v32
	v_sub_f32_e32 v32, v33, v144
	v_exp_f32_e32 v161, v32
	v_sub_f32_e32 v32, v50, v144
	v_exp_f32_e32 v168, v32
	v_sub_f32_e32 v32, v34, v144
	v_exp_f32_e32 v169, v32
	v_sub_f32_e32 v32, v51, v144
	v_exp_f32_e32 v170, v32
	v_sub_f32_e32 v32, v35, v144
	v_exp_f32_e32 v171, v32
	v_sub_f32_e32 v32, v52, v144
	v_exp_f32_e32 v49, v32
	v_sub_f32_e32 v32, v36, v144
	v_sub_f32_e32 v48, v48, v144
	v_exp_f32_e32 v51, v32
	v_sub_f32_e32 v32, v53, v144
	v_exp_f32_e32 v158, v48
	v_exp_f32_e32 v48, v32
	v_sub_f32_e32 v32, v37, v144
	v_exp_f32_e32 v50, v32
	v_sub_f32_e32 v32, v54, v144
	v_exp_f32_e32 v53, v32
	v_sub_f32_e32 v32, v38, v144
	v_exp_f32_e32 v151, v32
	v_sub_f32_e32 v32, v55, v144
	v_exp_f32_e32 v52, v32
	v_sub_f32_e32 v32, v39, v144
	v_exp_f32_e32 v150, v32
	v_sub_f32_e32 v32, v56, v144
	v_exp_f32_e32 v55, v32
	v_sub_f32_e32 v32, v40, v144
	v_exp_f32_e32 v153, v32
	v_sub_f32_e32 v32, v57, v144
	v_exp_f32_e32 v54, v32
	v_sub_f32_e32 v32, v41, v144
	v_exp_f32_e32 v152, v32
	v_sub_f32_e32 v32, v58, v144
	v_exp_f32_e32 v57, v32
	v_sub_f32_e32 v32, v42, v144
	v_exp_f32_e32 v155, v32
	v_sub_f32_e32 v32, v59, v144
	v_exp_f32_e32 v56, v32
	v_sub_f32_e32 v32, v43, v144
	v_exp_f32_e32 v154, v32
	v_sub_f32_e32 v32, v60, v144
	v_exp_f32_e32 v59, v32
	v_sub_f32_e32 v32, v44, v144
	v_exp_f32_e32 v157, v32
	v_sub_f32_e32 v32, v61, v144
	v_exp_f32_e32 v58, v32
	v_cvt_pk_bf16_f32 v32, v158, v160
	v_cvt_pk_bf16_f32 v33, v168, v170
	v_cvt_pk_bf16_f32 v34, v49, v48
	v_cvt_pk_bf16_f32 v35, v53, v52
	v_sub_f32_e32 v36, v62, v144
	v_mfma_f32_32x32x16_bf16 v[16:31], v[130:133], v[32:35], v[16:31]
	v_exp_f32_e32 v61, v36
	v_sub_f32_e32 v36, v63, v144
	v_exp_f32_e32 v60, v36
	v_cvt_pk_bf16_f32 v36, v55, v54
	v_cvt_pk_bf16_f32 v37, v57, v56
	v_cvt_pk_bf16_f32 v38, v59, v58
	v_cvt_pk_bf16_f32 v39, v61, v60
	s_waitcnt lgkmcnt(3)
	v_mfma_f32_32x32x16_bf16 v[0:15], v[118:121], v[32:35], v[0:15]
	v_sub_f32_e32 v40, v45, v144
	v_exp_f32_e32 v156, v40
	v_cvt_pk_bf16_f32 v40, v159, v161
	v_cvt_pk_bf16_f32 v41, v169, v171
	v_cvt_pk_bf16_f32 v42, v51, v50
	v_cvt_pk_bf16_f32 v43, v151, v150
	v_sub_f32_e32 v44, v46, v144
	v_mfma_f32_32x32x16_bf16 v[16:31], v[126:129], v[36:39], v[16:31]
	v_exp_f32_e32 v63, v44
	v_sub_f32_e32 v44, v47, v144
	v_exp_f32_e32 v62, v44
	v_cvt_pk_bf16_f32 v44, v153, v152
	v_cvt_pk_bf16_f32 v45, v155, v154
	v_cvt_pk_bf16_f32 v46, v157, v156
	v_cvt_pk_bf16_f32 v47, v63, v62
	v_mfma_f32_32x32x16_bf16 v[16:31], v[122:125], v[40:43], v[16:31]
	v_add_f32_e32 v32, v170, v171
	s_waitcnt lgkmcnt(2)
	v_mfma_f32_32x32x16_bf16 v[0:15], v[110:113], v[36:39], v[0:15]
	v_mfma_f32_32x32x16_bf16 v[16:31], v[114:117], v[44:47], v[16:31]
	v_add_f32_e32 v114, v158, v159
	v_add_f32_e32 v114, 0, v114
	v_add_f32_e32 v115, v160, v161
	v_add_f32_e32 v114, v115, v114
	v_add_f32_e32 v115, v168, v169
	v_add_f32_e32 v114, v115, v114
	v_add_f32_e32 v34, v32, v114
	s_waitcnt lgkmcnt(1)
	v_mfma_f32_32x32x16_bf16 v[0:15], v[106:109], v[40:43], v[0:15]
	v_add_f32_e64 v32, v48, v50
	v_add_f32_e64 v33, v49, v51
	v_add_f32_e32 v33, v33, v34
	v_add_f32_e32 v34, v32, v33
	v_add_f32_e64 v32, v52, v150
	v_add_f32_e64 v33, v53, v151
	v_add_f32_e32 v33, v33, v34
	v_add_f32_e32 v34, v32, v33
	v_pk_add_f32 v[32:33], v[54:55], v[152:153]
	s_waitcnt lgkmcnt(0)
	v_mfma_f32_32x32x16_bf16 v[0:15], v[102:105], v[44:47], v[0:15]
	v_add_f32_e32 v33, v33, v34
	v_add_f32_e32 v34, v32, v33
	v_add_f32_e64 v32, v56, v154
	v_add_f32_e64 v33, v57, v155
	v_add_f32_e32 v33, v33, v34
	v_add_f32_e32 v34, v32, v33
	v_pk_add_f32 v[32:33], v[58:59], v[156:157]
	s_nop 0
	v_add_f32_e32 v33, v33, v34
	v_add_f32_e32 v34, v32, v33
	v_pk_add_f32 v[32:33], v[60:61], v[62:63]
	s_nop 0
	v_add_f32_e32 v33, v33, v34
	v_add_f32_e32 v32, v32, v33
	v_add_f32_e32 v135, v135, v32
.LBB0_1157:
	s_add_i32 s71, s71, 1
	s_bitcmp1_b32 s71, 0
	s_cselect_b32 s66, 0x5800, 0
	s_add_i32 s72, s66, 0
	v_add_u32_e32 v32, s72, v134
	s_waitcnt vmcnt(1)
	ds_write_b128 v32, v[98:101]
	s_and_saveexec_b64 s[66:67], s[38:39]
	s_cbranch_execz .LBB0_1150
	v_add_u32_e32 v32, s72, v146
	s_waitcnt vmcnt(0)
	ds_write_b128 v32, v[90:93] offset:128
	s_branch .LBB0_1150
.LBB0_1159:
	s_cmp_gt_i32 s68, 2
	s_mov_b64 s[38:39], -1
	s_cbranch_scc1 .LBB0_1161
	v_mbcnt_hi_u32_b32 v98, -1, v214
	v_and_b32_e32 v32, 64, v98
	v_xor_b32_e32 v99, 32, v98
	v_add_u32_e32 v100, 64, v32
	s_mov_b64 s[38:39], 0
